# v26 + nt on the P1 (proj) and P10 (act) GEMM epilogue output stores
# baseline (speedup 1.0000x reference)
; __device__ __forceinline__ unsigned cvt_pk_bf16(float lo, float hi) { unsigned r; asm volatile("v_cvt_pk_bf16_f32 %0, %1, %2" : "=v"(r) : "v"(lo), "v"(hi)); return r; }
;     __device__ __forceinline__ void operator()(f32x4 (&acc)[2][2][4][2], const Unit& u, int wr, int wc, int fr, int fq) const {
;         const int row0 = u.orow + wr * 64 + fr, col0 = u.ocol + wc * 32 + 8 * fq;
;         f32x4 cv[2][2], bv[2][2];
; #pragma unroll
;         for (int bj = 0; bj < 2; ++bj)
; #pragma unroll
;             for (int n = 0; n < 2; ++n) { cv[bj][n] = *(const f32x4*)(cs + col0 + bj * HALF + 4 * n); bv[bj][n] = *(const f32x4*)(bw + col0 + bj * HALF + 4 * n); }
; #pragma unroll
;         for (int ai = 0; ai < 2; ++ai)
; #pragma unroll
;             for (int m = 0; m < 4; ++m) { const int row = row0 + ai * HALF + m * 16; bf16_t* rowp = O + (size_t)row * ldc + col0;
;                 const f32x2 st = *(const f32x2*)(ps + (size_t)row * 2); const float rs = st[1], nm = -st[0] * rs;
; #pragma unroll
;                 for (int bj = 0; bj < 2; ++bj) { const f32x4 v0 = acc[ai][bj][m][0] * rs + (cv[bj][0] * nm + bv[bj][0]), v1 = acc[ai][bj][m][1] * rs + (cv[bj][1] * nm + bv[bj][1]);
;                     u32x4 w; w.x = cvt_pk_bf16(v0[0], v0[1]); w.y = cvt_pk_bf16(v0[2], v0[3]); w.z = cvt_pk_bf16(v1[0], v1[1]); w.w = cvt_pk_bf16(v1[2], v1[3]);
;                     *(u32x4*)(rowp + bj * HALF) = w; } }
.LBB0_255:
	v_add_u32_e32 v164, s1, v172
	v_ashrrev_i32_e32 v165, 31, v164
	v_readlane_b32 s2, v249, 46
	v_add_u32_e32 v166, s0, v171
	v_lshlrev_b64 v[50:51], 2, v[164:165]
	v_readlane_b32 s3, v249, 47
	v_ashrrev_i32_e32 v167, 31, v166
	v_lshl_add_u64 v[58:59], s[64:65], 0, v[50:51]
	v_lshl_add_u64 v[74:75], s[2:3], 0, v[50:51]
	v_lshl_add_u64 v[184:185], v[166:167], 3, s[70:71]
	global_load_dwordx4 v[54:57], v[58:59], off offset:16
	global_load_dwordx4 v[70:73], v[58:59], off
	global_load_dwordx4 v[62:65], v[74:75], off offset:16
	global_load_dwordx4 v[78:81], v[74:75], off
	global_load_dwordx4 v[50:53], v[58:59], off offset:528
	global_load_dwordx4 v[66:69], v[58:59], off offset:512
	s_nop 0
	global_load_dwordx4 v[58:61], v[74:75], off offset:528
	s_nop 0
	global_load_dwordx4 v[74:77], v[74:75], off offset:512
	v_mov_b64_e32 v[162:163], s[74:75]
	global_load_dwordx2 v[230:231], v[184:185], off offset:128
	global_load_dwordx2 v[232:233], v[184:185], off offset:256
	global_load_dwordx2 v[234:235], v[184:185], off offset:384
	global_load_dwordx2 v[236:237], v[184:185], off offset:1024
	global_load_dwordx2 v[238:239], v[184:185], off offset:1152
	global_load_dwordx2 v[240:241], v[184:185], off offset:1280
	global_load_dwordx2 v[196:197], v[184:185], off offset:1408
	global_load_dwordx2 v[184:185], v[184:185], off
	s_movk_i32 s2, 0x3000
	v_mad_i64_i32 v[176:177], s[0:1], v166, s2, v[162:163]
	v_lshlrev_b64 v[164:165], 1, v[164:165]
	v_lshl_add_u64 v[176:177], v[176:177], 0, v[164:165]
	s_andn2_b64 vcc, exec, s[38:39]
	s_waitcnt vmcnt(0)
	v_mul_f32_e64 v178, v185, -v184
	v_pk_fma_f32 v[186:187], v[72:73], v[178:179], v[80:81] op_sel_hi:[1, 0, 1]
	v_pk_fma_f32 v[194:195], v[70:71], v[178:179], v[78:79] op_sel_hi:[1, 0, 1]
	v_pk_fma_f32 v[160:161], v[160:161], v[184:185], v[186:187] op_sel:[0, 1, 0]
	v_pk_fma_f32 v[158:159], v[158:159], v[184:185], v[194:195] op_sel:[0, 1, 0]
	v_pk_fma_f32 v[186:187], v[56:57], v[178:179], v[64:65] op_sel_hi:[1, 0, 1]
	v_pk_fma_f32 v[194:195], v[54:55], v[178:179], v[62:63] op_sel_hi:[1, 0, 1]
	v_pk_fma_f32 v[186:187], v[156:157], v[184:185], v[186:187] op_sel:[0, 1, 0]
	v_pk_fma_f32 v[156:157], v[154:155], v[184:185], v[194:195] op_sel:[0, 1, 0]
	v_cvt_pk_bf16_f32 v154, v158, v159
	v_cvt_pk_bf16_f32 v155, v160, v161
	s_nop 0
	v_cvt_pk_bf16_f32 v156, v156, v157
	v_cvt_pk_bf16_f32 v157, v186, v187
	global_store_dwordx4 v[176:177], v[154:157], off nt
	s_nop 1
	v_pk_fma_f32 v[154:155], v[68:69], v[178:179], v[76:77] op_sel_hi:[1, 0, 1]
	v_pk_fma_f32 v[156:157], v[66:67], v[178:179], v[74:75] op_sel_hi:[1, 0, 1]
	v_pk_fma_f32 v[152:153], v[152:153], v[184:185], v[154:155] op_sel:[0, 1, 0]
	v_pk_fma_f32 v[150:151], v[150:151], v[184:185], v[156:157] op_sel:[0, 1, 0]
	v_pk_fma_f32 v[154:155], v[52:53], v[178:179], v[60:61] op_sel_hi:[1, 0, 1]
	v_pk_fma_f32 v[156:157], v[50:51], v[178:179], v[58:59] op_sel_hi:[1, 0, 1]
	v_pk_fma_f32 v[154:155], v[148:149], v[184:185], v[154:155] op_sel:[0, 1, 0]
	v_pk_fma_f32 v[148:149], v[146:147], v[184:185], v[156:157] op_sel:[0, 1, 0]
	v_cvt_pk_bf16_f32 v146, v150, v151
	v_cvt_pk_bf16_f32 v147, v152, v153
	s_nop 0
	v_cvt_pk_bf16_f32 v148, v148, v149
	v_cvt_pk_bf16_f32 v149, v154, v155
	global_store_dwordx4 v[176:177], v[146:149], off offset:256 nt
	s_nop 1
	v_add_u32_e32 v146, 16, v166
	v_ashrrev_i32_e32 v147, 31, v146
	v_mad_i64_i32 v[148:149], s[0:1], v146, s2, v[162:163]
	v_lshl_add_u64 v[148:149], v[148:149], 0, v[164:165]
	v_mul_f32_e64 v150, v231, -v230
	v_pk_fma_f32 v[152:153], v[72:73], v[150:151], v[80:81] op_sel_hi:[1, 0, 1]
	v_pk_fma_f32 v[154:155], v[70:71], v[150:151], v[78:79] op_sel_hi:[1, 0, 1]
	v_pk_fma_f32 v[144:145], v[144:145], v[230:231], v[152:153] op_sel:[0, 1, 0]
	v_pk_fma_f32 v[142:143], v[142:143], v[230:231], v[154:155] op_sel:[0, 1, 0]
	v_pk_fma_f32 v[152:153], v[56:57], v[150:151], v[64:65] op_sel_hi:[1, 0, 1]
	v_pk_fma_f32 v[154:155], v[54:55], v[150:151], v[62:63] op_sel_hi:[1, 0, 1]
	v_pk_fma_f32 v[152:153], v[140:141], v[230:231], v[152:153] op_sel:[0, 1, 0]
	v_pk_fma_f32 v[140:141], v[138:139], v[230:231], v[154:155] op_sel:[0, 1, 0]
	v_cvt_pk_bf16_f32 v138, v142, v143
	v_cvt_pk_bf16_f32 v139, v144, v145
	s_nop 0
	v_cvt_pk_bf16_f32 v140, v140, v141
	v_cvt_pk_bf16_f32 v141, v152, v153
	global_store_dwordx4 v[148:149], v[138:141], off nt
	s_nop 1
	v_pk_fma_f32 v[138:139], v[68:69], v[150:151], v[76:77] op_sel_hi:[1, 0, 1]
	v_pk_fma_f32 v[140:141], v[66:67], v[150:151], v[74:75] op_sel_hi:[1, 0, 1]
	v_pk_fma_f32 v[136:137], v[136:137], v[230:231], v[138:139] op_sel:[0, 1, 0]
	v_pk_fma_f32 v[134:135], v[134:135], v[230:231], v[140:141] op_sel:[0, 1, 0]
	v_pk_fma_f32 v[138:139], v[52:53], v[150:151], v[60:61] op_sel_hi:[1, 0, 1]
	v_pk_fma_f32 v[140:141], v[50:51], v[150:151], v[58:59] op_sel_hi:[1, 0, 1]
	v_pk_fma_f32 v[138:139], v[132:133], v[230:231], v[138:139] op_sel:[0, 1, 0]
	v_pk_fma_f32 v[132:133], v[130:131], v[230:231], v[140:141] op_sel:[0, 1, 0]
	v_cvt_pk_bf16_f32 v130, v134, v135
	v_cvt_pk_bf16_f32 v131, v136, v137
	s_nop 0
	v_cvt_pk_bf16_f32 v132, v132, v133
	v_cvt_pk_bf16_f32 v133, v138, v139
	global_store_dwordx4 v[148:149], v[130:133], off offset:256 nt
	s_nop 1
	v_add_u32_e32 v130, 32, v166
	v_ashrrev_i32_e32 v131, 31, v130
	v_mad_i64_i32 v[132:133], s[0:1], v130, s2, v[162:163]
	v_lshl_add_u64 v[132:133], v[132:133], 0, v[164:165]
	v_mul_f32_e64 v134, v233, -v232
	v_pk_fma_f32 v[136:137], v[72:73], v[134:135], v[80:81] op_sel_hi:[1, 0, 1]
	v_pk_fma_f32 v[138:139], v[70:71], v[134:135], v[78:79] op_sel_hi:[1, 0, 1]
	v_pk_fma_f32 v[128:129], v[128:129], v[232:233], v[136:137] op_sel:[0, 1, 0]
; __device__ __forceinline__ unsigned cvt_pk_bf16(float lo, float hi) { unsigned r; asm volatile("v_cvt_pk_bf16_f32 %0, %1, %2" : "=v"(r) : "v"(lo), "v"(hi)); return r; }
;     __device__ __forceinline__ void operator()(f32x4 (&acc)[2][2][4][2], const Unit& u, int wr, int wc, int fr, int fq) const {
;     ...
;         for (int ai = 0; ai < 2; ++ai)
; #pragma unroll
;             for (int m = 0; m < 4; ++m) { const int row = row0 + ai * HALF + m * 16; bf16_t* rowp = O + (size_t)row * ldc + col0;
;                 const f32x2 st = *(const f32x2*)(ps + (size_t)row * 2); const float rs = st[1], nm = -st[0] * rs;
; #pragma unroll
;                 for (int bj = 0; bj < 2; ++bj) { const f32x4 v0 = acc[ai][bj][m][0] * rs + (cv[bj][0] * nm + bv[bj][0]), v1 = acc[ai][bj][m][1] * rs + (cv[bj][1] * nm + bv[bj][1]);
;                     u32x4 w; w.x = cvt_pk_bf16(v0[0], v0[1]); w.y = cvt_pk_bf16(v0[2], v0[3]); w.z = cvt_pk_bf16(v1[0], v1[1]); w.w = cvt_pk_bf16(v1[2], v1[3]);
;                     *(u32x4*)(rowp + bj * HALF) = w; } }
	v_pk_fma_f32 v[126:127], v[126:127], v[232:233], v[138:139] op_sel:[0, 1, 0]
	v_pk_fma_f32 v[136:137], v[56:57], v[134:135], v[64:65] op_sel_hi:[1, 0, 1]
	v_pk_fma_f32 v[138:139], v[54:55], v[134:135], v[62:63] op_sel_hi:[1, 0, 1]
	v_pk_fma_f32 v[136:137], v[124:125], v[232:233], v[136:137] op_sel:[0, 1, 0]
	v_pk_fma_f32 v[124:125], v[122:123], v[232:233], v[138:139] op_sel:[0, 1, 0]
	v_cvt_pk_bf16_f32 v122, v126, v127
	v_cvt_pk_bf16_f32 v123, v128, v129
	s_nop 0
	v_cvt_pk_bf16_f32 v124, v124, v125
	v_cvt_pk_bf16_f32 v125, v136, v137
	global_store_dwordx4 v[132:133], v[122:125], off nt
	s_nop 1
	v_pk_fma_f32 v[122:123], v[68:69], v[134:135], v[76:77] op_sel_hi:[1, 0, 1]
	v_pk_fma_f32 v[124:125], v[66:67], v[134:135], v[74:75] op_sel_hi:[1, 0, 1]
	v_pk_fma_f32 v[120:121], v[120:121], v[232:233], v[122:123] op_sel:[0, 1, 0]
	v_pk_fma_f32 v[118:119], v[118:119], v[232:233], v[124:125] op_sel:[0, 1, 0]
	v_pk_fma_f32 v[122:123], v[52:53], v[134:135], v[60:61] op_sel_hi:[1, 0, 1]
	v_pk_fma_f32 v[124:125], v[50:51], v[134:135], v[58:59] op_sel_hi:[1, 0, 1]
	v_pk_fma_f32 v[122:123], v[116:117], v[232:233], v[122:123] op_sel:[0, 1, 0]
	v_pk_fma_f32 v[116:117], v[114:115], v[232:233], v[124:125] op_sel:[0, 1, 0]
	v_cvt_pk_bf16_f32 v114, v118, v119
	v_cvt_pk_bf16_f32 v115, v120, v121
	s_nop 0
	v_cvt_pk_bf16_f32 v116, v116, v117
	v_cvt_pk_bf16_f32 v117, v122, v123
	global_store_dwordx4 v[132:133], v[114:117], off offset:256 nt
	s_nop 1
	v_add_u32_e32 v114, 48, v166
	v_ashrrev_i32_e32 v115, 31, v114
	v_mad_i64_i32 v[116:117], s[0:1], v114, s2, v[162:163]
	v_lshl_add_u64 v[116:117], v[116:117], 0, v[164:165]
	v_mul_f32_e64 v118, v235, -v234
	v_pk_fma_f32 v[120:121], v[72:73], v[118:119], v[80:81] op_sel_hi:[1, 0, 1]
	v_pk_fma_f32 v[122:123], v[70:71], v[118:119], v[78:79] op_sel_hi:[1, 0, 1]
	v_pk_fma_f32 v[112:113], v[112:113], v[234:235], v[120:121] op_sel:[0, 1, 0]
	v_pk_fma_f32 v[110:111], v[110:111], v[234:235], v[122:123] op_sel:[0, 1, 0]
	v_pk_fma_f32 v[120:121], v[56:57], v[118:119], v[64:65] op_sel_hi:[1, 0, 1]
	v_pk_fma_f32 v[122:123], v[54:55], v[118:119], v[62:63] op_sel_hi:[1, 0, 1]
	v_pk_fma_f32 v[120:121], v[108:109], v[234:235], v[120:121] op_sel:[0, 1, 0]
	v_pk_fma_f32 v[108:109], v[106:107], v[234:235], v[122:123] op_sel:[0, 1, 0]
	v_cvt_pk_bf16_f32 v106, v110, v111
	v_cvt_pk_bf16_f32 v107, v112, v113
	s_nop 0
	v_cvt_pk_bf16_f32 v108, v108, v109
	v_cvt_pk_bf16_f32 v109, v120, v121
	global_store_dwordx4 v[116:117], v[106:109], off nt
	s_nop 1
	v_pk_fma_f32 v[106:107], v[68:69], v[118:119], v[76:77] op_sel_hi:[1, 0, 1]
	v_pk_fma_f32 v[108:109], v[66:67], v[118:119], v[74:75] op_sel_hi:[1, 0, 1]
	v_pk_fma_f32 v[104:105], v[104:105], v[234:235], v[106:107] op_sel:[0, 1, 0]
	v_pk_fma_f32 v[102:103], v[102:103], v[234:235], v[108:109] op_sel:[0, 1, 0]
	v_pk_fma_f32 v[106:107], v[52:53], v[118:119], v[60:61] op_sel_hi:[1, 0, 1]
	v_pk_fma_f32 v[108:109], v[50:51], v[118:119], v[58:59] op_sel_hi:[1, 0, 1]
	v_pk_fma_f32 v[106:107], v[100:101], v[234:235], v[106:107] op_sel:[0, 1, 0]
	v_pk_fma_f32 v[100:101], v[98:99], v[234:235], v[108:109] op_sel:[0, 1, 0]
	v_cvt_pk_bf16_f32 v98, v102, v103
	v_cvt_pk_bf16_f32 v99, v104, v105
	s_nop 0
	v_cvt_pk_bf16_f32 v100, v100, v101
	v_cvt_pk_bf16_f32 v101, v106, v107
	global_store_dwordx4 v[116:117], v[98:101], off offset:256 nt
	s_nop 1
	v_add_u32_e32 v98, 0x80, v166
	v_ashrrev_i32_e32 v99, 31, v98
	v_mad_i64_i32 v[100:101], s[0:1], v98, s2, v[162:163]
	v_lshl_add_u64 v[100:101], v[100:101], 0, v[164:165]
	v_mul_f32_e64 v102, v237, -v236
	v_pk_fma_f32 v[104:105], v[72:73], v[102:103], v[80:81] op_sel_hi:[1, 0, 1]
	v_pk_fma_f32 v[106:107], v[70:71], v[102:103], v[78:79] op_sel_hi:[1, 0, 1]
	v_pk_fma_f32 v[96:97], v[96:97], v[236:237], v[104:105] op_sel:[0, 1, 0]
	v_pk_fma_f32 v[94:95], v[94:95], v[236:237], v[106:107] op_sel:[0, 1, 0]
	v_pk_fma_f32 v[104:105], v[56:57], v[102:103], v[64:65] op_sel_hi:[1, 0, 1]
	v_pk_fma_f32 v[106:107], v[54:55], v[102:103], v[62:63] op_sel_hi:[1, 0, 1]
	v_pk_fma_f32 v[104:105], v[92:93], v[236:237], v[104:105] op_sel:[0, 1, 0]
	v_pk_fma_f32 v[92:93], v[90:91], v[236:237], v[106:107] op_sel:[0, 1, 0]
	v_cvt_pk_bf16_f32 v90, v94, v95
	v_cvt_pk_bf16_f32 v91, v96, v97
	s_nop 0
	v_cvt_pk_bf16_f32 v92, v92, v93
	v_cvt_pk_bf16_f32 v93, v104, v105
	global_store_dwordx4 v[100:101], v[90:93], off nt
	s_nop 1
	v_pk_fma_f32 v[90:91], v[68:69], v[102:103], v[76:77] op_sel_hi:[1, 0, 1]
	v_pk_fma_f32 v[92:93], v[66:67], v[102:103], v[74:75] op_sel_hi:[1, 0, 1]
	v_pk_fma_f32 v[88:89], v[88:89], v[236:237], v[90:91] op_sel:[0, 1, 0]
	v_pk_fma_f32 v[86:87], v[86:87], v[236:237], v[92:93] op_sel:[0, 1, 0]
	v_pk_fma_f32 v[90:91], v[52:53], v[102:103], v[60:61] op_sel_hi:[1, 0, 1]
	v_pk_fma_f32 v[92:93], v[50:51], v[102:103], v[58:59] op_sel_hi:[1, 0, 1]
	v_pk_fma_f32 v[90:91], v[84:85], v[236:237], v[90:91] op_sel:[0, 1, 0]
	v_pk_fma_f32 v[84:85], v[82:83], v[236:237], v[92:93] op_sel:[0, 1, 0]
	v_cvt_pk_bf16_f32 v82, v86, v87
	v_cvt_pk_bf16_f32 v83, v88, v89
	s_nop 0
	v_cvt_pk_bf16_f32 v84, v84, v85
	v_cvt_pk_bf16_f32 v85, v90, v91
	global_store_dwordx4 v[100:101], v[82:85], off offset:256 nt
	s_nop 1
	v_add_u32_e32 v82, 0x90, v166
	v_ashrrev_i32_e32 v83, 31, v82
	v_mad_i64_i32 v[84:85], s[0:1], v82, s2, v[162:163]
; __device__ __forceinline__ unsigned cvt_pk_bf16(float lo, float hi) { unsigned r; asm volatile("v_cvt_pk_bf16_f32 %0, %1, %2" : "=v"(r) : "v"(lo), "v"(hi)); return r; }
;     __device__ __forceinline__ void operator()(f32x4 (&acc)[2][2][4][2], const Unit& u, int wr, int wc, int fr, int fq) const {
;     ...
;         for (int ai = 0; ai < 2; ++ai)
; #pragma unroll
;             for (int m = 0; m < 4; ++m) { const int row = row0 + ai * HALF + m * 16; bf16_t* rowp = O + (size_t)row * ldc + col0;
;                 const f32x2 st = *(const f32x2*)(ps + (size_t)row * 2); const float rs = st[1], nm = -st[0] * rs;
; #pragma unroll
;                 for (int bj = 0; bj < 2; ++bj) { const f32x4 v0 = acc[ai][bj][m][0] * rs + (cv[bj][0] * nm + bv[bj][0]), v1 = acc[ai][bj][m][1] * rs + (cv[bj][1] * nm + bv[bj][1]);
;                     u32x4 w; w.x = cvt_pk_bf16(v0[0], v0[1]); w.y = cvt_pk_bf16(v0[2], v0[3]); w.z = cvt_pk_bf16(v1[0], v1[1]); w.w = cvt_pk_bf16(v1[2], v1[3]);
;                     *(u32x4*)(rowp + bj * HALF) = w; } }
	v_lshl_add_u64 v[84:85], v[84:85], 0, v[164:165]
	v_mul_f32_e64 v86, v239, -v238
	v_pk_fma_f32 v[88:89], v[72:73], v[86:87], v[80:81] op_sel_hi:[1, 0, 1]
	v_pk_fma_f32 v[90:91], v[70:71], v[86:87], v[78:79] op_sel_hi:[1, 0, 1]
	v_pk_fma_f32 v[48:49], v[48:49], v[238:239], v[88:89] op_sel:[0, 1, 0]
	v_pk_fma_f32 v[46:47], v[46:47], v[238:239], v[90:91] op_sel:[0, 1, 0]
	v_pk_fma_f32 v[88:89], v[56:57], v[86:87], v[64:65] op_sel_hi:[1, 0, 1]
	v_pk_fma_f32 v[90:91], v[54:55], v[86:87], v[62:63] op_sel_hi:[1, 0, 1]
	v_pk_fma_f32 v[88:89], v[44:45], v[238:239], v[88:89] op_sel:[0, 1, 0]
	v_pk_fma_f32 v[44:45], v[42:43], v[238:239], v[90:91] op_sel:[0, 1, 0]
	v_cvt_pk_bf16_f32 v42, v46, v47
	v_cvt_pk_bf16_f32 v43, v48, v49
	s_nop 0
	v_cvt_pk_bf16_f32 v44, v44, v45
	v_cvt_pk_bf16_f32 v45, v88, v89
	global_store_dwordx4 v[84:85], v[42:45], off nt
	s_nop 1
	v_pk_fma_f32 v[42:43], v[68:69], v[86:87], v[76:77] op_sel_hi:[1, 0, 1]
	v_pk_fma_f32 v[44:45], v[66:67], v[86:87], v[74:75] op_sel_hi:[1, 0, 1]
	v_pk_fma_f32 v[40:41], v[40:41], v[238:239], v[42:43] op_sel:[0, 1, 0]
	v_pk_fma_f32 v[38:39], v[38:39], v[238:239], v[44:45] op_sel:[0, 1, 0]
	v_pk_fma_f32 v[42:43], v[52:53], v[86:87], v[60:61] op_sel_hi:[1, 0, 1]
	v_pk_fma_f32 v[44:45], v[50:51], v[86:87], v[58:59] op_sel_hi:[1, 0, 1]
	v_pk_fma_f32 v[42:43], v[36:37], v[238:239], v[42:43] op_sel:[0, 1, 0]
	v_pk_fma_f32 v[36:37], v[34:35], v[238:239], v[44:45] op_sel:[0, 1, 0]
	v_cvt_pk_bf16_f32 v34, v38, v39
	v_cvt_pk_bf16_f32 v35, v40, v41
	s_nop 0
	v_cvt_pk_bf16_f32 v36, v36, v37
	v_cvt_pk_bf16_f32 v37, v42, v43
	global_store_dwordx4 v[84:85], v[34:37], off offset:256 nt
	s_nop 1
	v_add_u32_e32 v34, 0xa0, v166
	v_ashrrev_i32_e32 v35, 31, v34
	v_mad_i64_i32 v[36:37], s[0:1], v34, s2, v[162:163]
	v_lshl_add_u64 v[36:37], v[36:37], 0, v[164:165]
	v_mul_f32_e64 v38, v241, -v240
	v_pk_fma_f32 v[40:41], v[72:73], v[38:39], v[80:81] op_sel_hi:[1, 0, 1]
	v_pk_fma_f32 v[42:43], v[70:71], v[38:39], v[78:79] op_sel_hi:[1, 0, 1]
	v_pk_fma_f32 v[32:33], v[32:33], v[240:241], v[40:41] op_sel:[0, 1, 0]
	v_pk_fma_f32 v[30:31], v[30:31], v[240:241], v[42:43] op_sel:[0, 1, 0]
	v_pk_fma_f32 v[40:41], v[56:57], v[38:39], v[64:65] op_sel_hi:[1, 0, 1]
	v_pk_fma_f32 v[42:43], v[54:55], v[38:39], v[62:63] op_sel_hi:[1, 0, 1]
	v_pk_fma_f32 v[40:41], v[28:29], v[240:241], v[40:41] op_sel:[0, 1, 0]
	v_pk_fma_f32 v[28:29], v[26:27], v[240:241], v[42:43] op_sel:[0, 1, 0]
	v_cvt_pk_bf16_f32 v26, v30, v31
	v_cvt_pk_bf16_f32 v27, v32, v33
	s_nop 0
	v_cvt_pk_bf16_f32 v28, v28, v29
	v_cvt_pk_bf16_f32 v29, v40, v41
	global_store_dwordx4 v[36:37], v[26:29], off nt
	s_nop 1
	v_pk_fma_f32 v[26:27], v[68:69], v[38:39], v[76:77] op_sel_hi:[1, 0, 1]
	v_pk_fma_f32 v[28:29], v[66:67], v[38:39], v[74:75] op_sel_hi:[1, 0, 1]
	v_pk_fma_f32 v[24:25], v[24:25], v[240:241], v[26:27] op_sel:[0, 1, 0]
	v_pk_fma_f32 v[22:23], v[22:23], v[240:241], v[28:29] op_sel:[0, 1, 0]
	v_pk_fma_f32 v[26:27], v[52:53], v[38:39], v[60:61] op_sel_hi:[1, 0, 1]
	v_pk_fma_f32 v[28:29], v[50:51], v[38:39], v[58:59] op_sel_hi:[1, 0, 1]
	v_pk_fma_f32 v[26:27], v[20:21], v[240:241], v[26:27] op_sel:[0, 1, 0]
	v_pk_fma_f32 v[20:21], v[18:19], v[240:241], v[28:29] op_sel:[0, 1, 0]
	v_cvt_pk_bf16_f32 v18, v22, v23
	v_cvt_pk_bf16_f32 v19, v24, v25
	s_nop 0
	v_cvt_pk_bf16_f32 v20, v20, v21
	v_cvt_pk_bf16_f32 v21, v26, v27
	global_store_dwordx4 v[36:37], v[18:21], off offset:256 nt
	s_nop 1
	v_add_u32_e32 v18, 0xb0, v166
	v_ashrrev_i32_e32 v19, 31, v18
	v_mad_i64_i32 v[20:21], s[0:1], v18, s2, v[162:163]
	v_lshl_add_u64 v[20:21], v[20:21], 0, v[164:165]
	s_mov_b64 s[2:3], -1
	v_mul_f32_e64 v22, v197, -v196
	v_pk_fma_f32 v[24:25], v[72:73], v[22:23], v[80:81] op_sel_hi:[1, 0, 1]
	v_pk_fma_f32 v[26:27], v[70:71], v[22:23], v[78:79] op_sel_hi:[1, 0, 1]
	v_pk_fma_f32 v[16:17], v[16:17], v[196:197], v[24:25] op_sel:[0, 1, 0]
	v_pk_fma_f32 v[14:15], v[14:15], v[196:197], v[26:27] op_sel:[0, 1, 0]
	v_pk_fma_f32 v[24:25], v[56:57], v[22:23], v[64:65] op_sel_hi:[1, 0, 1]
	v_pk_fma_f32 v[26:27], v[54:55], v[22:23], v[62:63] op_sel_hi:[1, 0, 1]
	v_pk_fma_f32 v[24:25], v[12:13], v[196:197], v[24:25] op_sel:[0, 1, 0]
	v_pk_fma_f32 v[12:13], v[10:11], v[196:197], v[26:27] op_sel:[0, 1, 0]
	v_cvt_pk_bf16_f32 v10, v14, v15
	v_cvt_pk_bf16_f32 v11, v16, v17
	s_nop 0
	v_cvt_pk_bf16_f32 v12, v12, v13
	v_cvt_pk_bf16_f32 v13, v24, v25
	global_store_dwordx4 v[20:21], v[10:13], off nt
	s_nop 1
	v_pk_fma_f32 v[10:11], v[68:69], v[22:23], v[76:77] op_sel_hi:[1, 0, 1]
	v_pk_fma_f32 v[12:13], v[66:67], v[22:23], v[74:75] op_sel_hi:[1, 0, 1]
	v_pk_fma_f32 v[8:9], v[8:9], v[196:197], v[10:11] op_sel:[0, 1, 0]
	v_pk_fma_f32 v[6:7], v[6:7], v[196:197], v[12:13] op_sel:[0, 1, 0]
	v_pk_fma_f32 v[10:11], v[52:53], v[22:23], v[60:61] op_sel_hi:[1, 0, 1]
	v_pk_fma_f32 v[12:13], v[50:51], v[22:23], v[58:59] op_sel_hi:[1, 0, 1]
	v_pk_fma_f32 v[10:11], v[4:5], v[196:197], v[10:11] op_sel:[0, 1, 0]
	v_pk_fma_f32 v[4:5], v[2:3], v[196:197], v[12:13] op_sel:[0, 1, 0]
	v_cvt_pk_bf16_f32 v2, v6, v7
	v_cvt_pk_bf16_f32 v3, v8, v9
	s_nop 0
	v_cvt_pk_bf16_f32 v4, v4, v5
	v_cvt_pk_bf16_f32 v5, v10, v11
	global_store_dwordx4 v[20:21], v[2:5], off offset:256 nt
	s_cbranch_vccnz .LBB0_248
	s_andn2_b64 vcc, exec, s[4:5]
	s_cbranch_vccnz .LBB0_247
	s_barrier
	s_branch .LBB0_247

;     __device__ __forceinline__ void operator()(f32x4 (&acc)[2][2][4][2], const Unit& u, int wr, int wc, int fr, int fq) const {
;     ...
; #pragma unroll
;             for (int ai = 0; ai < 2; ++ai)
; #pragma unroll
;                 for (int m = 0; m < 4; ++m) { const f32x2 st = *(const f32x2*)(ps + (size_t)(u.orow + ai * HALF + wr * 64 + m * 16 + fr) * 2); rsv[ai][m] = st[1]; nmv[ai][m] = -st[0] * st[1]; }
; #pragma unroll
;             for (int bj = 0; bj < 2; ++bj)
; #pragma unroll
;                 for (int n = 0; n < 2; ++n) { f32x4 cv = *(const f32x4*)(cs + colq + bj * HALF + 4 * n), bv = *(const f32x4*)(bw + colq + bj * HALF + 4 * n);
;                     asm volatile("" : "+v"(cv), "+v"(bv));
; #pragma unroll
;                     for (int ai = 0; ai < 2; ++ai)
; #pragma unroll
;                         for (int m = 0; m < 4; ++m) acc[ai][bj][m][n] = acc[ai][bj][m][n] * rsv[ai][m] + (cv * nmv[ai][m] + bv); }
;         }
; #pragma unroll
;         for (int ai = 0; ai < 2; ++ai) { const int run = (u.orow + ai * HALF + wr * 64) >> 6;
; #pragma unroll
;             for (int bj = 0; bj < 2; ++bj)
; #pragma unroll
;                 for (int n = 0; n < 2; ++n) {
;                     if (fr < 2) *(f32x4*)(rawH + ((size_t)(run * 2 + fr) * 2 + bj) * DFF + chb + 4 * n) = acc[ai][bj][0][n];
;                     if (fr >= 14) *(f32x4*)(rawT + ((size_t)(run * 2 + fr - 14) * 2 + bj) * DFF + chb + 4 * n) = acc[ai][bj][3][n]; } }
;         f32x4 w0, w1, w2, bb, nw0, nw1, nw2, nbb;
;         { w0 = *(const f32x4*)(cw + chb); w1 = *(const f32x4*)(cw + NUP + chb); w2 = *(const f32x4*)(cw + 2 * NUP + chb); bb = *(const f32x4*)(cb + chb); nw0 = w0; nw1 = w1; nw2 = w2; nbb = bb; }
; #pragma unroll
;         for (int blk = 0; blk < 8; ++blk) {
;             const int ai = blk >> 2, bj = (blk >> 1) & 1, n = blk & 1;
;             if (blk < 7) { int chb_ = chb; asm volatile("" : "+v"(chb_));
;                 const int cidx = (((blk + 1) >> 1) & 1) * DFF + chb_ + 4 * ((blk + 1) & 1);
;                 nw0 = *(const f32x4*)(cw + cidx); nw1 = *(const f32x4*)(cw + NUP + cidx); nw2 = *(const f32x4*)(cw + 2 * NUP + cidx); nbb = *(const f32x4*)(cb + cidx); }
.LBB0_1012:
	s_or_b64 exec, exec, s[2:3]
	v_mul_f32_e64 v184, v217, -v216
	v_mul_f32_e64 v186, v219, -v218
	v_pk_fma_f32 v[106:107], v[184:185], v[140:141], v[132:133] op_sel_hi:[0,1,1]
	v_mul_f32_e64 v194, v221, -v220
	v_pk_fma_f32 v[108:109], v[184:185], v[138:139], v[130:131] op_sel_hi:[0,1,1]
	v_pk_fma_f32 v[104:105], v[104:105], v[216:217], v[106:107] op_sel:[0,1,0]
	v_pk_fma_f32 v[106:107], v[186:187], v[140:141], v[132:133] op_sel_hi:[0,1,1]
	v_pk_fma_f32 v[114:115], v[186:187], v[138:139], v[130:131] op_sel_hi:[0,1,1]
	v_mul_f32_e64 v196, v223, -v222
	v_pk_fma_f32 v[102:103], v[102:103], v[216:217], v[108:109] op_sel:[0,1,0]
	v_pk_fma_f32 v[108:109], v[96:97], v[218:219], v[106:107] op_sel:[0,1,0]
	v_pk_fma_f32 v[106:107], v[94:95], v[218:219], v[114:115] op_sel:[0,1,0]
	v_pk_fma_f32 v[94:95], v[194:195], v[140:141], v[132:133] op_sel_hi:[0,1,1]
	v_pk_fma_f32 v[114:115], v[194:195], v[138:139], v[130:131] op_sel_hi:[0,1,1]
	v_pk_fma_f32 v[96:97], v[80:81], v[220:221], v[94:95] op_sel:[0,1,0]
	v_pk_fma_f32 v[80:81], v[196:197], v[138:139], v[130:131] op_sel_hi:[0,1,1]
	v_pk_fma_f32 v[94:95], v[78:79], v[220:221], v[114:115] op_sel:[0,1,0]
	v_pk_fma_f32 v[78:79], v[196:197], v[140:141], v[132:133] op_sel_hi:[0,1,1]
	v_pk_fma_f32 v[114:115], v[62:63], v[222:223], v[80:81] op_sel:[0,1,0]
	v_pk_fma_f32 v[62:63], v[184:185], v[176:177], v[172:173] op_sel_hi:[0,1,1]
	v_pk_fma_f32 v[116:117], v[64:65], v[222:223], v[78:79] op_sel:[0,1,0]
	v_pk_fma_f32 v[64:65], v[184:185], v[174:175], v[170:171] op_sel_hi:[0,1,1]
	v_pk_fma_f32 v[152:153], v[100:101], v[216:217], v[62:63] op_sel:[0,1,0]
	v_pk_fma_f32 v[62:63], v[186:187], v[176:177], v[172:173] op_sel_hi:[0,1,1]
	v_pk_fma_f32 v[150:151], v[98:99], v[216:217], v[64:65] op_sel:[0,1,0]
	v_pk_fma_f32 v[64:65], v[186:187], v[174:175], v[170:171] op_sel_hi:[0,1,1]
	v_pk_fma_f32 v[156:157], v[92:93], v[218:219], v[62:63] op_sel:[0,1,0]
	v_pk_fma_f32 v[62:63], v[194:195], v[176:177], v[172:173] op_sel_hi:[0,1,1]
	v_pk_fma_f32 v[154:155], v[90:91], v[218:219], v[64:65] op_sel:[0,1,0]
	v_pk_fma_f32 v[64:65], v[194:195], v[174:175], v[170:171] op_sel_hi:[0,1,1]
	v_pk_fma_f32 v[80:81], v[44:45], v[220:221], v[62:63] op_sel:[0,1,0]
	v_pk_fma_f32 v[44:45], v[196:197], v[174:175], v[170:171] op_sel_hi:[0,1,1]
	v_pk_fma_f32 v[78:79], v[42:43], v[220:221], v[64:65] op_sel:[0,1,0]
	v_pk_fma_f32 v[42:43], v[196:197], v[176:177], v[172:173] op_sel_hi:[0,1,1]
	v_pk_fma_f32 v[90:91], v[34:35], v[222:223], v[44:45] op_sel:[0,1,0]
	v_pk_fma_f32 v[34:35], v[184:185], v[168:169], v[128:129] op_sel_hi:[0,1,1]
	v_pk_fma_f32 v[92:93], v[36:37], v[222:223], v[42:43] op_sel:[0,1,0]
	v_pk_fma_f32 v[36:37], v[184:185], v[166:167], v[126:127] op_sel_hi:[0,1,1]
	v_pk_fma_f32 v[140:141], v[88:89], v[216:217], v[34:35] op_sel:[0,1,0]
	v_pk_fma_f32 v[34:35], v[186:187], v[168:169], v[128:129] op_sel_hi:[0,1,1]
	v_pk_fma_f32 v[138:139], v[86:87], v[216:217], v[36:37] op_sel:[0,1,0]
	v_pk_fma_f32 v[36:37], v[186:187], v[166:167], v[126:127] op_sel_hi:[0,1,1]
	v_pk_fma_f32 v[100:101], v[72:73], v[218:219], v[34:35] op_sel:[0,1,0]
	v_pk_fma_f32 v[34:35], v[194:195], v[168:169], v[128:129] op_sel_hi:[0,1,1]
	v_pk_fma_f32 v[98:99], v[70:71], v[218:219], v[36:37] op_sel:[0,1,0]
	v_pk_fma_f32 v[36:37], v[194:195], v[166:167], v[126:127] op_sel_hi:[0,1,1]
	v_pk_fma_f32 v[44:45], v[32:33], v[220:221], v[34:35] op_sel:[0,1,0]
	v_pk_fma_f32 v[32:33], v[196:197], v[166:167], v[126:127] op_sel_hi:[0,1,1]
	v_pk_fma_f32 v[42:43], v[30:31], v[220:221], v[36:37] op_sel:[0,1,0]
	v_pk_fma_f32 v[30:31], v[196:197], v[168:169], v[128:129] op_sel_hi:[0,1,1]
	v_pk_fma_f32 v[62:63], v[14:15], v[222:223], v[32:33] op_sel:[0,1,0]
	v_pk_fma_f32 v[14:15], v[184:185], v[164:165], v[160:161] op_sel_hi:[0,1,1]
	v_pk_fma_f32 v[64:65], v[16:17], v[222:223], v[30:31] op_sel:[0,1,0]
	v_pk_fma_f32 v[16:17], v[184:185], v[162:163], v[158:159] op_sel_hi:[0,1,1]
	v_pk_fma_f32 v[128:129], v[68:69], v[216:217], v[14:15] op_sel:[0,1,0]
	v_pk_fma_f32 v[14:15], v[186:187], v[164:165], v[160:161] op_sel_hi:[0,1,1]
	v_pk_fma_f32 v[126:127], v[66:67], v[216:217], v[16:17] op_sel:[0,1,0]
	v_pk_fma_f32 v[16:17], v[186:187], v[162:163], v[158:159] op_sel_hi:[0,1,1]
	v_pk_fma_f32 v[132:133], v[56:57], v[218:219], v[14:15] op_sel:[0,1,0]
	v_pk_fma_f32 v[14:15], v[194:195], v[164:165], v[160:161] op_sel_hi:[0,1,1]
	v_pk_fma_f32 v[130:131], v[54:55], v[218:219], v[16:17] op_sel:[0,1,0]
	v_pk_fma_f32 v[30:31], v[194:195], v[162:163], v[158:159] op_sel_hi:[0,1,1]
	v_pk_fma_f32 v[16:17], v[12:13], v[220:221], v[14:15] op_sel:[0,1,0]
	v_pk_fma_f32 v[12:13], v[196:197], v[162:163], v[158:159] op_sel_hi:[0,1,1]
	v_pk_fma_f32 v[14:15], v[10:11], v[220:221], v[30:31] op_sel:[0,1,0]
	v_pk_fma_f32 v[10:11], v[196:197], v[164:165], v[160:161] op_sel_hi:[0,1,1]
	v_pk_fma_f32 v[30:31], v[2:3], v[222:223], v[12:13] op_sel:[0,1,0]
	v_lshlrev_b64 v[2:3], 2, v[214:215]
	v_pk_fma_f32 v[32:33], v[4:5], v[222:223], v[10:11] op_sel:[0,1,0]
	v_lshl_add_u64 v[4:5], s[36:37], 0, v[2:3]
	v_lshl_add_u64 v[34:35], s[52:53], 0, v[2:3]
	v_lshl_add_u64 v[36:37], s[54:55], 0, v[2:3]
	v_lshl_add_u64 v[2:3], s[48:49], 0, v[2:3]
	global_load_dwordx4 v[10:13], v[2:3], off
	global_load_dwordx4 v[86:89], v[36:37], off
	global_load_dwordx4 v[170:173], v[34:35], off
	global_load_dwordx4 v[54:57], v[4:5], off
	v_mov_b32_e32 v2, v214
	v_mov_b32_e32 v70, v1
	v_add_u32_e32 v4, 4, v2
	v_ashrrev_i32_e32 v5, 31, v4
	v_ashrrev_i32_e32 v3, 31, v2
	v_lshlrev_b64 v[4:5], 2, v[4:5]
	v_lshlrev_b64 v[2:3], 2, v[2:3]
	v_lshl_add_u64 v[36:37], s[52:53], 0, v[4:5]
	v_lshl_add_u64 v[4:5], s[54:55], 0, v[4:5]
	v_lshl_add_u64 v[34:35], s[36:37], 0, v[2:3]
	v_lshl_add_u64 v[2:3], s[48:49], 0, v[2:3]
	global_load_dwordx4 v[158:161], v[4:5], off
	global_load_dwordx4 v[166:169], v[36:37], off
	global_load_dwordx4 v[66:69], v[2:3], off offset:16
	global_load_dwordx4 v[162:165], v[34:35], off offset:16
	v_mov_b64_e32 v[2:3], v[106:107]
	v_mov_b64_e32 v[4:5], v[108:109]
	v_mov_b32_e32 v34, v1
	v_mov_b32_e32 v36, v1
	v_mov_b32_e32 v35, v1
	v_mov_b32_e32 v37, v1
	v_mov_b32_e32 v71, v1
	v_mov_b32_e32 v72, v1
	v_mov_b32_e32 v73, v1
	s_mov_b32 s2, s29
	s_mov_b32 s3, s29
	s_mov_b32 s0, s29
	s_waitcnt vmcnt(4)
; template <int CTRL> __device__ __forceinline__ float dppf(float old, float src) { return __int_as_float(__builtin_amdgcn_update_dpp(__float_as_int(old), __float_as_int(src), CTRL, 0xf, 0xf, false)); }
;     __device__ __forceinline__ void operator()(f32x4 (&acc)[2][2][4][2], const Unit& u, int wr, int wc, int fr, int fq) const {
;     ...
;         for (int blk = 0; blk < 8; ++blk) {
;             const int ai = blk >> 2, bj = (blk >> 1) & 1, n = blk & 1;
;             if (blk < 7) { int chb_ = chb; asm volatile("" : "+v"(chb_));
;                 const int cidx = (((blk + 1) >> 1) & 1) * DFF + chb_ + 4 * ((blk + 1) & 1);
;                 nw0 = *(const f32x4*)(cw + cidx); nw1 = *(const f32x4*)(cw + NUP + cidx); nw2 = *(const f32x4*)(cw + 2 * NUP + cidx); nbb = *(const f32x4*)(cb + cidx); }
;             asm volatile("" : "+v"(w0), "+v"(w1), "+v"(w2), "+v"(bb));
; #pragma unroll
;             for (int m = 3; m >= 0; --m) {
;                 f32x4 v = acc[ai][bj][m][n]; f32x4 pv = (m > 0) ? acc[ai][bj][m > 0 ? m - 1 : 0][n] : (f32x4){0.f, 0.f, 0.f, 0.f};
;                 asm volatile("" : "+v"(v), "+v"(pv));
;                 f32x4 r;
; #pragma unroll
;                 for (int e = 0; e < 4; ++e) {
;                     const float o1 = dppf<0x121>(0.f, pv[e]), o2 = dppf<0x122>(0.f, pv[e]);
;                     const float p1 = dppf<0x111>(o1, v[e]), p2 = dppf<0x112>(o2, v[e]);
;                     r[e] = w2[e] * v[e] + w1[e] * p1 + w0[e] * p2 + bb[e];
;                 }
;                 asm volatile("" : "+v"(r));
;                 acc[ai][bj][m][n] = r;
;             }
	s_mov_b32 s1, s29
	v_mov_b32_e32 v174, v1
	v_mov_b32_dpp v34, v2 row_ror:1 row_mask:0xf bank_mask:0xf
	v_mov_b32_dpp v36, v2 row_ror:2 row_mask:0xf bank_mask:0xf
	v_mov_b32_dpp v35, v3 row_ror:1 row_mask:0xf bank_mask:0xf
	v_mov_b32_dpp v37, v3 row_ror:2 row_mask:0xf bank_mask:0xf
	v_mov_b32_e32 v2, v1
	v_mov_b32_e32 v3, v1
	v_mov_b32_dpp v34, v146 row_shr:1 row_mask:0xf bank_mask:0xf
	v_mov_b32_dpp v2, v4 row_ror:1 row_mask:0xf bank_mask:0xf
	v_mov_b32_dpp v3, v5 row_ror:1 row_mask:0xf bank_mask:0xf
	v_mov_b32_dpp v35, v147 row_shr:1 row_mask:0xf bank_mask:0xf
	v_mov_b32_dpp v2, v148 row_shr:1 row_mask:0xf bank_mask:0xf
	v_mov_b32_dpp v3, v149 row_shr:1 row_mask:0xf bank_mask:0xf
	v_mov_b32_dpp v70, v4 row_ror:2 row_mask:0xf bank_mask:0xf
	v_mov_b32_dpp v71, v5 row_ror:2 row_mask:0xf bank_mask:0xf
	v_pk_mul_f32 v[4:5], v[170:171], v[34:35]
	v_pk_mul_f32 v[2:3], v[172:173], v[2:3]
	v_mov_b32_dpp v36, v146 row_shr:2 row_mask:0xf bank_mask:0xf
	v_mov_b32_dpp v37, v147 row_shr:2 row_mask:0xf bank_mask:0xf
	v_mov_b32_dpp v70, v148 row_shr:2 row_mask:0xf bank_mask:0xf
	v_mov_b32_dpp v71, v149 row_shr:2 row_mask:0xf bank_mask:0xf
	v_pk_fma_f32 v[2:3], v[88:89], v[148:149], v[2:3]
	v_pk_fma_f32 v[4:5], v[86:87], v[146:147], v[4:5]
	v_pk_fma_f32 v[2:3], v[56:57], v[70:71], v[2:3]
	v_pk_fma_f32 v[34:35], v[54:55], v[36:37], v[4:5]
	v_pk_add_f32 v[4:5], v[12:13], v[2:3]
	v_pk_add_f32 v[2:3], v[10:11], v[34:35]
	v_mov_b64_e32 v[34:35], v[102:103]
	v_mov_b64_e32 v[36:37], v[104:105]
	v_mov_b32_e32 v70, v1
	v_mov_b32_e32 v71, v1
	v_mov_b32_dpp v72, v34 row_ror:2 row_mask:0xf bank_mask:0xf
	v_mov_b32_dpp v70, v34 row_ror:1 row_mask:0xf bank_mask:0xf
	v_mov_b32_dpp v71, v35 row_ror:1 row_mask:0xf bank_mask:0xf
	v_mov_b32_dpp v73, v35 row_ror:2 row_mask:0xf bank_mask:0xf
	v_mov_b32_e32 v34, v1
	v_mov_b32_e32 v35, v1
	v_mov_b32_dpp v70, v106 row_shr:1 row_mask:0xf bank_mask:0xf
	v_mov_b32_dpp v34, v36 row_ror:1 row_mask:0xf bank_mask:0xf
	v_mov_b32_dpp v35, v37 row_ror:1 row_mask:0xf bank_mask:0xf
	v_mov_b32_dpp v71, v107 row_shr:1 row_mask:0xf bank_mask:0xf
	v_mov_b32_e32 v146, v1
	v_mov_b32_dpp v34, v108 row_shr:1 row_mask:0xf bank_mask:0xf
	v_mov_b32_e32 v147, v1
	v_mov_b32_dpp v35, v109 row_shr:1 row_mask:0xf bank_mask:0xf
	v_mov_b32_dpp v146, v36 row_ror:2 row_mask:0xf bank_mask:0xf
	v_mov_b32_dpp v147, v37 row_ror:2 row_mask:0xf bank_mask:0xf
	v_pk_mul_f32 v[36:37], v[170:171], v[70:71]
	v_pk_mul_f32 v[34:35], v[172:173], v[34:35]
	v_mov_b32_dpp v72, v106 row_shr:2 row_mask:0xf bank_mask:0xf
	v_mov_b32_dpp v73, v107 row_shr:2 row_mask:0xf bank_mask:0xf
	v_mov_b32_dpp v146, v108 row_shr:2 row_mask:0xf bank_mask:0xf
	v_mov_b32_dpp v147, v109 row_shr:2 row_mask:0xf bank_mask:0xf
	v_pk_fma_f32 v[34:35], v[88:89], v[108:109], v[34:35]
	v_pk_fma_f32 v[36:37], v[86:87], v[106:107], v[36:37]
	v_pk_fma_f32 v[34:35], v[56:57], v[146:147], v[34:35]
	v_pk_fma_f32 v[70:71], v[54:55], v[72:73], v[36:37]
	v_pk_add_f32 v[36:37], v[12:13], v[34:35]
	v_pk_add_f32 v[34:35], v[10:11], v[70:71]
	v_mov_b64_e32 v[70:71], v[134:135]
	v_mov_b64_e32 v[72:73], v[136:137]
	v_mov_b32_e32 v106, v1
	v_mov_b32_e32 v108, v1
	v_mov_b32_e32 v107, v1
	v_mov_b32_e32 v109, v1
	v_mov_b32_dpp v106, v70 row_ror:1 row_mask:0xf bank_mask:0xf
	v_mov_b32_dpp v108, v70 row_ror:2 row_mask:0xf bank_mask:0xf
	v_mov_b32_dpp v107, v71 row_ror:1 row_mask:0xf bank_mask:0xf
	v_mov_b32_dpp v109, v71 row_ror:2 row_mask:0xf bank_mask:0xf
	v_mov_b32_e32 v70, v1
	v_mov_b32_e32 v71, v1
	v_mov_b32_dpp v106, v102 row_shr:1 row_mask:0xf bank_mask:0xf
	v_mov_b32_dpp v70, v72 row_ror:1 row_mask:0xf bank_mask:0xf
	v_mov_b32_dpp v71, v73 row_ror:1 row_mask:0xf bank_mask:0xf
	v_mov_b32_dpp v107, v103 row_shr:1 row_mask:0xf bank_mask:0xf
	v_mov_b32_e32 v146, v1
	v_mov_b32_dpp v70, v104 row_shr:1 row_mask:0xf bank_mask:0xf
	v_mov_b32_e32 v147, v1
	v_mov_b32_dpp v71, v105 row_shr:1 row_mask:0xf bank_mask:0xf
	v_mov_b32_dpp v146, v72 row_ror:2 row_mask:0xf bank_mask:0xf
	v_mov_b32_dpp v147, v73 row_ror:2 row_mask:0xf bank_mask:0xf
	v_pk_mul_f32 v[72:73], v[170:171], v[106:107]
	v_pk_mul_f32 v[70:71], v[172:173], v[70:71]
	v_mov_b32_dpp v108, v102 row_shr:2 row_mask:0xf bank_mask:0xf
	v_mov_b32_dpp v109, v103 row_shr:2 row_mask:0xf bank_mask:0xf
	v_mov_b32_dpp v146, v104 row_shr:2 row_mask:0xf bank_mask:0xf
	v_mov_b32_dpp v147, v105 row_shr:2 row_mask:0xf bank_mask:0xf
	v_pk_fma_f32 v[70:71], v[88:89], v[104:105], v[70:71]
	v_pk_fma_f32 v[72:73], v[86:87], v[102:103], v[72:73]
	v_pk_fma_f32 v[70:71], v[56:57], v[146:147], v[70:71]
	v_pk_fma_f32 v[102:103], v[54:55], v[108:109], v[72:73]
	v_pk_add_f32 v[72:73], v[12:13], v[70:71]
	v_pk_add_f32 v[70:71], v[10:11], v[102:103]
	v_mov_b64_e32 v[104:105], s[2:3]
	v_mov_b64_e32 v[102:103], s[0:1]
	v_mov_b32_e32 v146, v1
	v_mov_b32_e32 v148, v1
	v_mov_b32_e32 v147, v1
	v_mov_b32_e32 v149, v1
	v_mov_b32_dpp v146, v102 row_ror:1 row_mask:0xf bank_mask:0xf
	v_mov_b32_dpp v148, v102 row_ror:2 row_mask:0xf bank_mask:0xf
	v_mov_b32_dpp v147, v103 row_ror:1 row_mask:0xf bank_mask:0xf
	v_mov_b32_dpp v149, v103 row_ror:2 row_mask:0xf bank_mask:0xf
	v_mov_b32_e32 v102, v1
	v_mov_b32_e32 v103, v1
	v_mov_b32_dpp v146, v134 row_shr:1 row_mask:0xf bank_mask:0xf
	v_mov_b32_dpp v102, v104 row_ror:1 row_mask:0xf bank_mask:0xf
	v_mov_b32_dpp v103, v105 row_ror:1 row_mask:0xf bank_mask:0xf
	v_mov_b32_dpp v147, v135 row_shr:1 row_mask:0xf bank_mask:0xf
	v_mov_b32_dpp v102, v136 row_shr:1 row_mask:0xf bank_mask:0xf
	v_mov_b32_e32 v175, v1
	v_mov_b32_dpp v103, v137 row_shr:1 row_mask:0xf bank_mask:0xf
	v_mov_b32_dpp v174, v104 row_ror:2 row_mask:0xf bank_mask:0xf
	v_mov_b32_dpp v175, v105 row_ror:2 row_mask:0xf bank_mask:0xf
	v_pk_mul_f32 v[102:103], v[172:173], v[102:103]
	v_pk_mul_f32 v[104:105], v[170:171], v[146:147]
	v_mov_b32_dpp v148, v134 row_shr:2 row_mask:0xf bank_mask:0xf
	v_mov_b32_dpp v149, v135 row_shr:2 row_mask:0xf bank_mask:0xf
	v_mov_b32_dpp v174, v136 row_shr:2 row_mask:0xf bank_mask:0xf
	v_mov_b32_dpp v175, v137 row_shr:2 row_mask:0xf bank_mask:0xf
	v_pk_fma_f32 v[88:89], v[88:89], v[136:137], v[102:103]
	v_pk_fma_f32 v[86:87], v[86:87], v[134:135], v[104:105]
	v_pk_fma_f32 v[56:57], v[56:57], v[174:175], v[88:89]
	v_pk_fma_f32 v[54:55], v[54:55], v[148:149], v[86:87]
	v_pk_add_f32 v[104:105], v[12:13], v[56:57]
	v_pk_add_f32 v[102:103], v[10:11], v[54:55]
	v_mov_b32_e32 v10, v214
	v_mov_b32_e32 v86, v1
	v_add_u32_e32 v10, 0x1600, v10
	v_ashrrev_i32_e32 v11, 31, v10
	v_lshlrev_b64 v[10:11], 2, v[10:11]
	v_lshl_add_u64 v[12:13], s[36:37], 0, v[10:11]
	v_lshl_add_u64 v[54:55], s[52:53], 0, v[10:11]
	v_lshl_add_u64 v[56:57], s[54:55], 0, v[10:11]
	v_lshl_add_u64 v[10:11], s[48:49], 0, v[10:11]
	global_load_dwordx4 v[134:137], v[10:11], off
	global_load_dwordx4 v[170:173], v[56:57], off
	global_load_dwordx4 v[174:177], v[54:55], off
	global_load_dwordx4 v[146:149], v[12:13], off
	v_mov_b64_e32 v[10:11], v[154:155]
	v_mov_b64_e32 v[12:13], v[156:157]
	s_waitcnt vmcnt(4)
; template <int CTRL> __device__ __forceinline__ float dppf(float old, float src) { return __int_as_float(__builtin_amdgcn_update_dpp(__float_as_int(old), __float_as_int(src), CTRL, 0xf, 0xf, false)); }
;     __device__ __forceinline__ void operator()(f32x4 (&acc)[2][2][4][2], const Unit& u, int wr, int wc, int fr, int fq) const {
;     ...
;         for (int blk = 0; blk < 8; ++blk) {
;             const int ai = blk >> 2, bj = (blk >> 1) & 1, n = blk & 1;
;             if (blk < 7) { int chb_ = chb; asm volatile("" : "+v"(chb_));
;                 const int cidx = (((blk + 1) >> 1) & 1) * DFF + chb_ + 4 * ((blk + 1) & 1);
;                 nw0 = *(const f32x4*)(cw + cidx); nw1 = *(const f32x4*)(cw + NUP + cidx); nw2 = *(const f32x4*)(cw + 2 * NUP + cidx); nbb = *(const f32x4*)(cb + cidx); }
;             asm volatile("" : "+v"(w0), "+v"(w1), "+v"(w2), "+v"(bb));
; #pragma unroll
;             for (int m = 3; m >= 0; --m) {
;                 f32x4 v = acc[ai][bj][m][n]; f32x4 pv = (m > 0) ? acc[ai][bj][m > 0 ? m - 1 : 0][n] : (f32x4){0.f, 0.f, 0.f, 0.f};
;                 asm volatile("" : "+v"(v), "+v"(pv));
;                 f32x4 r;
; #pragma unroll
;                 for (int e = 0; e < 4; ++e) {
;                     const float o1 = dppf<0x121>(0.f, pv[e]), o2 = dppf<0x122>(0.f, pv[e]);
;                     const float p1 = dppf<0x111>(o1, v[e]), p2 = dppf<0x112>(o2, v[e]);
;                     r[e] = w2[e] * v[e] + w1[e] * p1 + w0[e] * p2 + bb[e];
;                 }
;                 asm volatile("" : "+v"(r));
;                 acc[ai][bj][m][n] = r;
;             }
	v_mov_b32_e32 v54, v1
	v_mov_b32_e32 v56, v1
	v_mov_b32_e32 v55, v1
	v_mov_b32_e32 v57, v1
	v_mov_b32_dpp v54, v10 row_ror:1 row_mask:0xf bank_mask:0xf
	v_mov_b32_dpp v56, v10 row_ror:2 row_mask:0xf bank_mask:0xf
	v_mov_b32_dpp v55, v11 row_ror:1 row_mask:0xf bank_mask:0xf
	v_mov_b32_dpp v57, v11 row_ror:2 row_mask:0xf bank_mask:0xf
	v_mov_b32_e32 v10, v1
	v_mov_b32_e32 v11, v1
	v_mov_b32_dpp v54, v142 row_shr:1 row_mask:0xf bank_mask:0xf
	v_mov_b32_dpp v10, v12 row_ror:1 row_mask:0xf bank_mask:0xf
	v_mov_b32_dpp v11, v13 row_ror:1 row_mask:0xf bank_mask:0xf
	v_mov_b32_dpp v55, v143 row_shr:1 row_mask:0xf bank_mask:0xf
	v_mov_b32_dpp v10, v144 row_shr:1 row_mask:0xf bank_mask:0xf
	v_mov_b32_e32 v87, v1
	v_mov_b32_dpp v11, v145 row_shr:1 row_mask:0xf bank_mask:0xf
	v_mov_b32_dpp v86, v12 row_ror:2 row_mask:0xf bank_mask:0xf
	v_mov_b32_dpp v87, v13 row_ror:2 row_mask:0xf bank_mask:0xf
	v_pk_mul_f32 v[12:13], v[166:167], v[54:55]
	v_pk_mul_f32 v[10:11], v[168:169], v[10:11]
	v_mov_b32_dpp v56, v142 row_shr:2 row_mask:0xf bank_mask:0xf
	v_mov_b32_dpp v57, v143 row_shr:2 row_mask:0xf bank_mask:0xf
	v_mov_b32_dpp v86, v144 row_shr:2 row_mask:0xf bank_mask:0xf
	v_mov_b32_dpp v87, v145 row_shr:2 row_mask:0xf bank_mask:0xf
	v_pk_fma_f32 v[10:11], v[160:161], v[144:145], v[10:11]
	v_pk_fma_f32 v[12:13], v[158:159], v[142:143], v[12:13]
	v_pk_fma_f32 v[10:11], v[164:165], v[86:87], v[10:11]
	v_pk_fma_f32 v[54:55], v[162:163], v[56:57], v[12:13]
	v_pk_add_f32 v[12:13], v[68:69], v[10:11]
	v_pk_add_f32 v[10:11], v[66:67], v[54:55]
	v_mov_b64_e32 v[54:55], v[150:151]
	v_mov_b64_e32 v[56:57], v[152:153]
	v_mov_b32_e32 v86, v1
	v_mov_b32_e32 v88, v1
	v_mov_b32_e32 v87, v1
	v_mov_b32_e32 v89, v1
	v_mov_b32_dpp v86, v54 row_ror:1 row_mask:0xf bank_mask:0xf
	v_mov_b32_dpp v88, v54 row_ror:2 row_mask:0xf bank_mask:0xf
	v_mov_b32_dpp v87, v55 row_ror:1 row_mask:0xf bank_mask:0xf
	v_mov_b32_dpp v89, v55 row_ror:2 row_mask:0xf bank_mask:0xf
	v_mov_b32_e32 v54, v1
	v_mov_b32_e32 v55, v1
	v_mov_b32_dpp v86, v154 row_shr:1 row_mask:0xf bank_mask:0xf
	v_mov_b32_dpp v54, v56 row_ror:1 row_mask:0xf bank_mask:0xf
	v_mov_b32_dpp v55, v57 row_ror:1 row_mask:0xf bank_mask:0xf
	v_mov_b32_dpp v87, v155 row_shr:1 row_mask:0xf bank_mask:0xf
	v_mov_b32_e32 v142, v1
	v_mov_b32_dpp v54, v156 row_shr:1 row_mask:0xf bank_mask:0xf
	v_mov_b32_e32 v143, v1
	v_mov_b32_dpp v55, v157 row_shr:1 row_mask:0xf bank_mask:0xf
	v_mov_b32_dpp v142, v56 row_ror:2 row_mask:0xf bank_mask:0xf
	v_mov_b32_dpp v143, v57 row_ror:2 row_mask:0xf bank_mask:0xf
	v_pk_mul_f32 v[56:57], v[166:167], v[86:87]
	v_pk_mul_f32 v[54:55], v[168:169], v[54:55]
	v_mov_b32_dpp v88, v154 row_shr:2 row_mask:0xf bank_mask:0xf
	v_mov_b32_dpp v89, v155 row_shr:2 row_mask:0xf bank_mask:0xf
	v_mov_b32_dpp v142, v156 row_shr:2 row_mask:0xf bank_mask:0xf
	v_mov_b32_dpp v143, v157 row_shr:2 row_mask:0xf bank_mask:0xf
	v_pk_fma_f32 v[54:55], v[160:161], v[156:157], v[54:55]
	v_pk_fma_f32 v[56:57], v[158:159], v[154:155], v[56:57]
	v_pk_fma_f32 v[54:55], v[164:165], v[142:143], v[54:55]
	v_pk_fma_f32 v[86:87], v[162:163], v[88:89], v[56:57]
	v_pk_add_f32 v[56:57], v[68:69], v[54:55]
	v_pk_add_f32 v[54:55], v[66:67], v[86:87]
	v_mov_b64_e32 v[86:87], v[118:119]
	v_mov_b64_e32 v[88:89], v[120:121]
	v_mov_b32_e32 v142, v1
	v_mov_b32_e32 v144, v1
	v_mov_b32_e32 v143, v1
	v_mov_b32_e32 v145, v1
	v_mov_b32_dpp v142, v86 row_ror:1 row_mask:0xf bank_mask:0xf
	v_mov_b32_dpp v144, v86 row_ror:2 row_mask:0xf bank_mask:0xf
	v_mov_b32_dpp v143, v87 row_ror:1 row_mask:0xf bank_mask:0xf
	v_mov_b32_dpp v145, v87 row_ror:2 row_mask:0xf bank_mask:0xf
	v_mov_b32_e32 v86, v1
	v_mov_b32_e32 v87, v1
	v_mov_b32_dpp v142, v150 row_shr:1 row_mask:0xf bank_mask:0xf
	v_mov_b32_dpp v86, v88 row_ror:1 row_mask:0xf bank_mask:0xf
	v_mov_b32_dpp v87, v89 row_ror:1 row_mask:0xf bank_mask:0xf
	v_mov_b32_dpp v143, v151 row_shr:1 row_mask:0xf bank_mask:0xf
	v_mov_b32_e32 v154, v1
	v_mov_b32_dpp v86, v152 row_shr:1 row_mask:0xf bank_mask:0xf
	v_mov_b32_e32 v155, v1
	v_mov_b32_dpp v87, v153 row_shr:1 row_mask:0xf bank_mask:0xf
	v_mov_b32_dpp v154, v88 row_ror:2 row_mask:0xf bank_mask:0xf
	v_mov_b32_dpp v155, v89 row_ror:2 row_mask:0xf bank_mask:0xf
	v_pk_mul_f32 v[88:89], v[166:167], v[142:143]
	v_pk_mul_f32 v[86:87], v[168:169], v[86:87]
	v_mov_b32_dpp v144, v150 row_shr:2 row_mask:0xf bank_mask:0xf
	v_mov_b32_dpp v145, v151 row_shr:2 row_mask:0xf bank_mask:0xf
	v_mov_b32_dpp v154, v152 row_shr:2 row_mask:0xf bank_mask:0xf
	v_mov_b32_dpp v155, v153 row_shr:2 row_mask:0xf bank_mask:0xf
	v_pk_fma_f32 v[86:87], v[160:161], v[152:153], v[86:87]
	v_pk_fma_f32 v[88:89], v[158:159], v[150:151], v[88:89]
	v_pk_fma_f32 v[86:87], v[164:165], v[154:155], v[86:87]
	v_pk_fma_f32 v[142:143], v[162:163], v[144:145], v[88:89]
	v_pk_add_f32 v[88:89], v[68:69], v[86:87]
	v_pk_add_f32 v[86:87], v[66:67], v[142:143]
	v_mov_b64_e32 v[144:145], s[2:3]
	v_mov_b64_e32 v[142:143], s[0:1]
	v_mov_b32_e32 v150, v1
	v_mov_b32_e32 v152, v1
	v_mov_b32_e32 v151, v1
	v_mov_b32_e32 v153, v1
	v_mov_b32_dpp v150, v142 row_ror:1 row_mask:0xf bank_mask:0xf
	v_mov_b32_dpp v152, v142 row_ror:2 row_mask:0xf bank_mask:0xf
	v_mov_b32_dpp v151, v143 row_ror:1 row_mask:0xf bank_mask:0xf
	v_mov_b32_dpp v153, v143 row_ror:2 row_mask:0xf bank_mask:0xf
	v_mov_b32_e32 v142, v1
	v_mov_b32_e32 v143, v1
	v_mov_b32_dpp v150, v118 row_shr:1 row_mask:0xf bank_mask:0xf
	v_mov_b32_dpp v142, v144 row_ror:1 row_mask:0xf bank_mask:0xf
	v_mov_b32_dpp v143, v145 row_ror:1 row_mask:0xf bank_mask:0xf
	v_mov_b32_dpp v151, v119 row_shr:1 row_mask:0xf bank_mask:0xf
	v_mov_b32_e32 v154, v1
	v_mov_b32_dpp v142, v120 row_shr:1 row_mask:0xf bank_mask:0xf
; template <int CTRL> __device__ __forceinline__ float dppf(float old, float src) { return __int_as_float(__builtin_amdgcn_update_dpp(__float_as_int(old), __float_as_int(src), CTRL, 0xf, 0xf, false)); }
;     __device__ __forceinline__ void operator()(f32x4 (&acc)[2][2][4][2], const Unit& u, int wr, int wc, int fr, int fq) const {
;     ...
;         for (int blk = 0; blk < 8; ++blk) {
;             const int ai = blk >> 2, bj = (blk >> 1) & 1, n = blk & 1;
;             if (blk < 7) { int chb_ = chb; asm volatile("" : "+v"(chb_));
;                 const int cidx = (((blk + 1) >> 1) & 1) * DFF + chb_ + 4 * ((blk + 1) & 1);
;                 nw0 = *(const f32x4*)(cw + cidx); nw1 = *(const f32x4*)(cw + NUP + cidx); nw2 = *(const f32x4*)(cw + 2 * NUP + cidx); nbb = *(const f32x4*)(cb + cidx); }
;             asm volatile("" : "+v"(w0), "+v"(w1), "+v"(w2), "+v"(bb));
; #pragma unroll
;             for (int m = 3; m >= 0; --m) {
;                 f32x4 v = acc[ai][bj][m][n]; f32x4 pv = (m > 0) ? acc[ai][bj][m > 0 ? m - 1 : 0][n] : (f32x4){0.f, 0.f, 0.f, 0.f};
;                 asm volatile("" : "+v"(v), "+v"(pv));
;                 f32x4 r;
; #pragma unroll
;                 for (int e = 0; e < 4; ++e) {
;                     const float o1 = dppf<0x121>(0.f, pv[e]), o2 = dppf<0x122>(0.f, pv[e]);
;                     const float p1 = dppf<0x111>(o1, v[e]), p2 = dppf<0x112>(o2, v[e]);
;                     r[e] = w2[e] * v[e] + w1[e] * p1 + w0[e] * p2 + bb[e];
;                 }
;                 asm volatile("" : "+v"(r));
;                 acc[ai][bj][m][n] = r;
;             }
	v_mov_b32_e32 v155, v1
	v_mov_b32_dpp v143, v121 row_shr:1 row_mask:0xf bank_mask:0xf
	v_mov_b32_dpp v154, v144 row_ror:2 row_mask:0xf bank_mask:0xf
	v_mov_b32_dpp v155, v145 row_ror:2 row_mask:0xf bank_mask:0xf
	v_pk_mul_f32 v[144:145], v[166:167], v[150:151]
	v_pk_mul_f32 v[142:143], v[168:169], v[142:143]
	v_mov_b32_dpp v152, v118 row_shr:2 row_mask:0xf bank_mask:0xf
	v_mov_b32_dpp v153, v119 row_shr:2 row_mask:0xf bank_mask:0xf
	v_mov_b32_dpp v154, v120 row_shr:2 row_mask:0xf bank_mask:0xf
	v_mov_b32_dpp v155, v121 row_shr:2 row_mask:0xf bank_mask:0xf
	v_pk_fma_f32 v[120:121], v[160:161], v[120:121], v[142:143]
	v_pk_fma_f32 v[118:119], v[158:159], v[118:119], v[144:145]
	v_pk_fma_f32 v[120:121], v[164:165], v[154:155], v[120:121]
	v_pk_fma_f32 v[118:119], v[162:163], v[152:153], v[118:119]
	v_pk_add_f32 v[120:121], v[68:69], v[120:121]
	v_pk_add_f32 v[118:119], v[66:67], v[118:119]
	v_mov_b32_e32 v66, v214
	v_mov_b32_e32 v158, v1
	v_add_u32_e32 v66, 0x1604, v66
	v_ashrrev_i32_e32 v67, 31, v66
	v_lshlrev_b64 v[66:67], 2, v[66:67]
	v_lshl_add_u64 v[68:69], s[36:37], 0, v[66:67]
	v_lshl_add_u64 v[142:143], s[52:53], 0, v[66:67]
	v_lshl_add_u64 v[144:145], s[54:55], 0, v[66:67]
	v_lshl_add_u64 v[66:67], s[48:49], 0, v[66:67]
	global_load_dwordx4 v[150:153], v[66:67], off
	global_load_dwordx4 v[162:165], v[144:145], off
	global_load_dwordx4 v[166:169], v[142:143], off
	global_load_dwordx4 v[154:157], v[68:69], off
	v_mov_b64_e32 v[66:67], v[98:99]
	v_mov_b64_e32 v[68:69], v[100:101]
	s_waitcnt vmcnt(4)
	v_mov_b32_e32 v142, v1
	v_mov_b32_e32 v144, v1
	v_mov_b32_e32 v143, v1
	v_mov_b32_e32 v145, v1
	v_mov_b32_dpp v142, v66 row_ror:1 row_mask:0xf bank_mask:0xf
	v_mov_b32_dpp v144, v66 row_ror:2 row_mask:0xf bank_mask:0xf
	v_mov_b32_dpp v143, v67 row_ror:1 row_mask:0xf bank_mask:0xf
	v_mov_b32_dpp v145, v67 row_ror:2 row_mask:0xf bank_mask:0xf
	v_mov_b32_e32 v66, v1
	v_mov_b32_e32 v67, v1
	v_mov_b32_dpp v142, v122 row_shr:1 row_mask:0xf bank_mask:0xf
	v_mov_b32_dpp v66, v68 row_ror:1 row_mask:0xf bank_mask:0xf
	v_mov_b32_dpp v67, v69 row_ror:1 row_mask:0xf bank_mask:0xf
	v_mov_b32_dpp v143, v123 row_shr:1 row_mask:0xf bank_mask:0xf
	v_mov_b32_dpp v66, v124 row_shr:1 row_mask:0xf bank_mask:0xf
	v_mov_b32_e32 v159, v1
	v_mov_b32_dpp v67, v125 row_shr:1 row_mask:0xf bank_mask:0xf
	v_mov_b32_dpp v158, v68 row_ror:2 row_mask:0xf bank_mask:0xf
	v_mov_b32_dpp v159, v69 row_ror:2 row_mask:0xf bank_mask:0xf
	v_pk_mul_f32 v[66:67], v[176:177], v[66:67]
	v_pk_mul_f32 v[68:69], v[174:175], v[142:143]
	v_mov_b32_dpp v144, v122 row_shr:2 row_mask:0xf bank_mask:0xf
	v_mov_b32_dpp v145, v123 row_shr:2 row_mask:0xf bank_mask:0xf
	v_mov_b32_dpp v158, v124 row_shr:2 row_mask:0xf bank_mask:0xf
	v_mov_b32_dpp v159, v125 row_shr:2 row_mask:0xf bank_mask:0xf
	v_pk_fma_f32 v[66:67], v[172:173], v[124:125], v[66:67]
	v_pk_fma_f32 v[68:69], v[170:171], v[122:123], v[68:69]
	v_pk_fma_f32 v[66:67], v[148:149], v[158:159], v[66:67]
	v_pk_fma_f32 v[122:123], v[146:147], v[144:145], v[68:69]
	v_pk_add_f32 v[68:69], v[136:137], v[66:67]
	v_pk_add_f32 v[66:67], v[134:135], v[122:123]
	v_mov_b64_e32 v[122:123], v[138:139]
	v_mov_b64_e32 v[124:125], v[140:141]
	v_mov_b32_e32 v142, v1
	v_mov_b32_e32 v144, v1
	v_mov_b32_e32 v143, v1
	v_mov_b32_e32 v145, v1
	v_mov_b32_dpp v142, v122 row_ror:1 row_mask:0xf bank_mask:0xf
	v_mov_b32_dpp v144, v122 row_ror:2 row_mask:0xf bank_mask:0xf
	v_mov_b32_dpp v143, v123 row_ror:1 row_mask:0xf bank_mask:0xf
	v_mov_b32_dpp v145, v123 row_ror:2 row_mask:0xf bank_mask:0xf
	v_mov_b32_e32 v122, v1
	v_mov_b32_e32 v123, v1
	v_mov_b32_dpp v142, v98 row_shr:1 row_mask:0xf bank_mask:0xf
	v_mov_b32_dpp v122, v124 row_ror:1 row_mask:0xf bank_mask:0xf
	v_mov_b32_dpp v123, v125 row_ror:1 row_mask:0xf bank_mask:0xf
	v_mov_b32_dpp v143, v99 row_shr:1 row_mask:0xf bank_mask:0xf
	v_mov_b32_e32 v158, v1
	v_mov_b32_dpp v122, v100 row_shr:1 row_mask:0xf bank_mask:0xf
	v_mov_b32_e32 v159, v1
	v_mov_b32_dpp v123, v101 row_shr:1 row_mask:0xf bank_mask:0xf
	v_mov_b32_dpp v158, v124 row_ror:2 row_mask:0xf bank_mask:0xf
	v_mov_b32_dpp v159, v125 row_ror:2 row_mask:0xf bank_mask:0xf
	v_pk_mul_f32 v[124:125], v[174:175], v[142:143]
	v_pk_mul_f32 v[122:123], v[176:177], v[122:123]
	v_mov_b32_dpp v144, v98 row_shr:2 row_mask:0xf bank_mask:0xf
	v_mov_b32_dpp v145, v99 row_shr:2 row_mask:0xf bank_mask:0xf
	v_mov_b32_dpp v158, v100 row_shr:2 row_mask:0xf bank_mask:0xf
	v_mov_b32_dpp v159, v101 row_shr:2 row_mask:0xf bank_mask:0xf
	v_pk_fma_f32 v[100:101], v[172:173], v[100:101], v[122:123]
	v_pk_fma_f32 v[98:99], v[170:171], v[98:99], v[124:125]
	v_pk_fma_f32 v[100:101], v[148:149], v[158:159], v[100:101]
	v_pk_fma_f32 v[98:99], v[146:147], v[144:145], v[98:99]
	v_mov_b64_e32 v[124:125], v[112:113]
	v_pk_add_f32 v[100:101], v[136:137], v[100:101]
	v_pk_add_f32 v[98:99], v[134:135], v[98:99]
	v_mov_b64_e32 v[122:123], v[110:111]
	v_mov_b32_e32 v142, v1
	v_mov_b32_e32 v144, v1
	v_mov_b32_e32 v143, v1
	v_mov_b32_e32 v145, v1
	v_mov_b32_dpp v142, v122 row_ror:1 row_mask:0xf bank_mask:0xf
	v_mov_b32_dpp v144, v122 row_ror:2 row_mask:0xf bank_mask:0xf
	v_mov_b32_dpp v143, v123 row_ror:1 row_mask:0xf bank_mask:0xf
	v_mov_b32_dpp v145, v123 row_ror:2 row_mask:0xf bank_mask:0xf
	v_mov_b32_e32 v122, v1
	v_mov_b32_e32 v123, v1
	v_mov_b32_dpp v142, v138 row_shr:1 row_mask:0xf bank_mask:0xf
	v_mov_b32_dpp v122, v124 row_ror:1 row_mask:0xf bank_mask:0xf
	v_mov_b32_dpp v123, v125 row_ror:1 row_mask:0xf bank_mask:0xf
	v_mov_b32_dpp v143, v139 row_shr:1 row_mask:0xf bank_mask:0xf
	v_mov_b32_e32 v158, v1
	v_mov_b32_dpp v122, v140 row_shr:1 row_mask:0xf bank_mask:0xf
	v_mov_b32_e32 v159, v1
; template <int CTRL> __device__ __forceinline__ float dppf(float old, float src) { return __int_as_float(__builtin_amdgcn_update_dpp(__float_as_int(old), __float_as_int(src), CTRL, 0xf, 0xf, false)); }
;     __device__ __forceinline__ void operator()(f32x4 (&acc)[2][2][4][2], const Unit& u, int wr, int wc, int fr, int fq) const {
;     ...
;         f32x4 w0, w1, w2, bb, nw0, nw1, nw2, nbb;
;         { w0 = *(const f32x4*)(cw + chb); w1 = *(const f32x4*)(cw + NUP + chb); w2 = *(const f32x4*)(cw + 2 * NUP + chb); bb = *(const f32x4*)(cb + chb); nw0 = w0; nw1 = w1; nw2 = w2; nbb = bb; }
; #pragma unroll
;         for (int blk = 0; blk < 8; ++blk) {
;             const int ai = blk >> 2, bj = (blk >> 1) & 1, n = blk & 1;
;             if (blk < 7) { int chb_ = chb; asm volatile("" : "+v"(chb_));
;                 const int cidx = (((blk + 1) >> 1) & 1) * DFF + chb_ + 4 * ((blk + 1) & 1);
;                 nw0 = *(const f32x4*)(cw + cidx); nw1 = *(const f32x4*)(cw + NUP + cidx); nw2 = *(const f32x4*)(cw + 2 * NUP + cidx); nbb = *(const f32x4*)(cb + cidx); }
;             asm volatile("" : "+v"(w0), "+v"(w1), "+v"(w2), "+v"(bb));
; #pragma unroll
;             for (int m = 3; m >= 0; --m) {
;                 f32x4 v = acc[ai][bj][m][n]; f32x4 pv = (m > 0) ? acc[ai][bj][m > 0 ? m - 1 : 0][n] : (f32x4){0.f, 0.f, 0.f, 0.f};
;                 asm volatile("" : "+v"(v), "+v"(pv));
;                 f32x4 r;
; #pragma unroll
;                 for (int e = 0; e < 4; ++e) {
;                     const float o1 = dppf<0x121>(0.f, pv[e]), o2 = dppf<0x122>(0.f, pv[e]);
;                     const float p1 = dppf<0x111>(o1, v[e]), p2 = dppf<0x112>(o2, v[e]);
;                     r[e] = w2[e] * v[e] + w1[e] * p1 + w0[e] * p2 + bb[e];
;                 }
;                 asm volatile("" : "+v"(r));
;                 acc[ai][bj][m][n] = r;
;             }
;             w0 = nw0; w1 = nw1; w2 = nw2; bb = nbb;
;         }
	v_mov_b32_dpp v123, v141 row_shr:1 row_mask:0xf bank_mask:0xf
	v_mov_b32_dpp v158, v124 row_ror:2 row_mask:0xf bank_mask:0xf
	v_mov_b32_dpp v159, v125 row_ror:2 row_mask:0xf bank_mask:0xf
	v_pk_mul_f32 v[122:123], v[176:177], v[122:123]
	v_pk_mul_f32 v[124:125], v[174:175], v[142:143]
	v_mov_b32_dpp v144, v138 row_shr:2 row_mask:0xf bank_mask:0xf
	v_mov_b32_dpp v145, v139 row_shr:2 row_mask:0xf bank_mask:0xf
	v_mov_b32_dpp v158, v140 row_shr:2 row_mask:0xf bank_mask:0xf
	v_mov_b32_dpp v159, v141 row_shr:2 row_mask:0xf bank_mask:0xf
	v_pk_fma_f32 v[122:123], v[172:173], v[140:141], v[122:123]
	v_pk_fma_f32 v[124:125], v[170:171], v[138:139], v[124:125]
	v_pk_fma_f32 v[122:123], v[148:149], v[158:159], v[122:123]
	v_pk_fma_f32 v[138:139], v[146:147], v[144:145], v[124:125]
	v_pk_add_f32 v[124:125], v[136:137], v[122:123]
	v_pk_add_f32 v[122:123], v[134:135], v[138:139]
	v_mov_b64_e32 v[140:141], s[2:3]
	v_mov_b64_e32 v[138:139], s[0:1]
	v_mov_b32_e32 v142, v1
	v_mov_b32_e32 v144, v1
	v_mov_b32_e32 v143, v1
	v_mov_b32_e32 v145, v1
	v_mov_b32_dpp v142, v138 row_ror:1 row_mask:0xf bank_mask:0xf
	v_mov_b32_dpp v144, v138 row_ror:2 row_mask:0xf bank_mask:0xf
	v_mov_b32_dpp v143, v139 row_ror:1 row_mask:0xf bank_mask:0xf
	v_mov_b32_dpp v145, v139 row_ror:2 row_mask:0xf bank_mask:0xf
	v_mov_b32_e32 v138, v1
	v_mov_b32_e32 v139, v1
	v_mov_b32_dpp v142, v110 row_shr:1 row_mask:0xf bank_mask:0xf
	v_mov_b32_dpp v138, v140 row_ror:1 row_mask:0xf bank_mask:0xf
	v_mov_b32_dpp v139, v141 row_ror:1 row_mask:0xf bank_mask:0xf
	v_mov_b32_dpp v143, v111 row_shr:1 row_mask:0xf bank_mask:0xf
	v_mov_b32_e32 v158, v1
	v_mov_b32_dpp v138, v112 row_shr:1 row_mask:0xf bank_mask:0xf
	v_mov_b32_e32 v159, v1
	v_mov_b32_dpp v139, v113 row_shr:1 row_mask:0xf bank_mask:0xf
	v_mov_b32_dpp v158, v140 row_ror:2 row_mask:0xf bank_mask:0xf
	v_mov_b32_dpp v159, v141 row_ror:2 row_mask:0xf bank_mask:0xf
	v_pk_mul_f32 v[138:139], v[176:177], v[138:139]
	v_pk_mul_f32 v[140:141], v[174:175], v[142:143]
	v_mov_b32_dpp v144, v110 row_shr:2 row_mask:0xf bank_mask:0xf
	v_mov_b32_dpp v145, v111 row_shr:2 row_mask:0xf bank_mask:0xf
	v_mov_b32_dpp v158, v112 row_shr:2 row_mask:0xf bank_mask:0xf
	v_mov_b32_dpp v159, v113 row_shr:2 row_mask:0xf bank_mask:0xf
	v_pk_fma_f32 v[112:113], v[172:173], v[112:113], v[138:139]
	v_pk_fma_f32 v[110:111], v[170:171], v[110:111], v[140:141]
	v_pk_fma_f32 v[112:113], v[148:149], v[158:159], v[112:113]
	v_pk_fma_f32 v[110:111], v[146:147], v[144:145], v[110:111]
	v_pk_add_f32 v[136:137], v[136:137], v[112:113]
	v_pk_add_f32 v[134:135], v[134:135], v[110:111]
	v_mov_b32_e32 v110, v214
	v_mov_b32_e32 v170, v1
	v_ashrrev_i32_e32 v111, 31, v110
	v_lshlrev_b64 v[110:111], 2, v[110:111]
	v_lshl_add_u64 v[112:113], s[36:37], 0, v[110:111]
	v_lshl_add_u64 v[142:143], s[52:53], 0, v[110:111]
	v_lshl_add_u64 v[144:145], s[54:55], 0, v[110:111]
	v_lshl_add_u64 v[110:111], s[48:49], 0, v[110:111]
	global_load_dwordx4 v[138:141], v[110:111], off
	global_load_dwordx4 v[146:149], v[144:145], off
	global_load_dwordx4 v[158:161], v[142:143], off
	s_nop 0
	global_load_dwordx4 v[142:145], v[112:113], off
	v_mov_b64_e32 v[110:111], v[130:131]
	v_mov_b64_e32 v[112:113], v[132:133]
	s_waitcnt vmcnt(4)
	v_mov_b32_e32 v172, v1
	v_mov_b32_e32 v171, v1
	v_mov_b32_e32 v173, v1
	v_mov_b32_dpp v170, v110 row_ror:1 row_mask:0xf bank_mask:0xf
	v_mov_b32_dpp v172, v110 row_ror:2 row_mask:0xf bank_mask:0xf
	v_mov_b32_dpp v171, v111 row_ror:1 row_mask:0xf bank_mask:0xf
	v_mov_b32_dpp v173, v111 row_ror:2 row_mask:0xf bank_mask:0xf
	v_mov_b32_e32 v110, v1
	v_mov_b32_e32 v111, v1
	v_mov_b32_dpp v170, v82 row_shr:1 row_mask:0xf bank_mask:0xf
	v_mov_b32_dpp v110, v112 row_ror:1 row_mask:0xf bank_mask:0xf
	v_mov_b32_dpp v111, v113 row_ror:1 row_mask:0xf bank_mask:0xf
	v_mov_b32_dpp v171, v83 row_shr:1 row_mask:0xf bank_mask:0xf
	v_mov_b32_e32 v174, v1
	v_mov_b32_dpp v110, v84 row_shr:1 row_mask:0xf bank_mask:0xf
	v_mov_b32_e32 v175, v1
	v_mov_b32_dpp v111, v85 row_shr:1 row_mask:0xf bank_mask:0xf
	v_mov_b32_dpp v174, v112 row_ror:2 row_mask:0xf bank_mask:0xf
	v_mov_b32_dpp v175, v113 row_ror:2 row_mask:0xf bank_mask:0xf
	v_pk_mul_f32 v[110:111], v[168:169], v[110:111]
	v_pk_mul_f32 v[112:113], v[166:167], v[170:171]
	v_mov_b32_dpp v172, v82 row_shr:2 row_mask:0xf bank_mask:0xf
	v_mov_b32_dpp v173, v83 row_shr:2 row_mask:0xf bank_mask:0xf
	v_mov_b32_dpp v174, v84 row_shr:2 row_mask:0xf bank_mask:0xf
	v_mov_b32_dpp v175, v85 row_shr:2 row_mask:0xf bank_mask:0xf
	v_pk_fma_f32 v[84:85], v[164:165], v[84:85], v[110:111]
	v_pk_fma_f32 v[82:83], v[162:163], v[82:83], v[112:113]
	v_pk_fma_f32 v[84:85], v[156:157], v[174:175], v[84:85]
	v_pk_fma_f32 v[82:83], v[154:155], v[172:173], v[82:83]
	v_mov_b64_e32 v[110:111], v[126:127]
	v_pk_add_f32 v[84:85], v[152:153], v[84:85]
	v_pk_add_f32 v[82:83], v[150:151], v[82:83]
	v_mov_b64_e32 v[112:113], v[128:129]
	v_mov_b32_e32 v170, v1
	v_mov_b32_e32 v172, v1
	v_mov_b32_e32 v171, v1
	v_mov_b32_e32 v173, v1
	v_mov_b32_dpp v170, v110 row_ror:1 row_mask:0xf bank_mask:0xf
	v_mov_b32_dpp v172, v110 row_ror:2 row_mask:0xf bank_mask:0xf
	v_mov_b32_dpp v171, v111 row_ror:1 row_mask:0xf bank_mask:0xf
	v_mov_b32_dpp v173, v111 row_ror:2 row_mask:0xf bank_mask:0xf
	v_mov_b32_e32 v110, v1
	v_mov_b32_e32 v111, v1
	v_mov_b32_dpp v170, v130 row_shr:1 row_mask:0xf bank_mask:0xf
	v_mov_b32_dpp v110, v112 row_ror:1 row_mask:0xf bank_mask:0xf
	v_mov_b32_dpp v111, v113 row_ror:1 row_mask:0xf bank_mask:0xf
	v_mov_b32_dpp v171, v131 row_shr:1 row_mask:0xf bank_mask:0xf
	v_mov_b32_e32 v174, v1
	v_mov_b32_dpp v110, v132 row_shr:1 row_mask:0xf bank_mask:0xf
	v_mov_b32_e32 v175, v1
; template <int CTRL> __device__ __forceinline__ float dppf(float old, float src) { return __int_as_float(__builtin_amdgcn_update_dpp(__float_as_int(old), __float_as_int(src), CTRL, 0xf, 0xf, false)); }
;     __device__ __forceinline__ void operator()(f32x4 (&acc)[2][2][4][2], const Unit& u, int wr, int wc, int fr, int fq) const {
;     ...
;         f32x4 w0, w1, w2, bb, nw0, nw1, nw2, nbb;
;         { w0 = *(const f32x4*)(cw + chb); w1 = *(const f32x4*)(cw + NUP + chb); w2 = *(const f32x4*)(cw + 2 * NUP + chb); bb = *(const f32x4*)(cb + chb); nw0 = w0; nw1 = w1; nw2 = w2; nbb = bb; }
; #pragma unroll
;         for (int blk = 0; blk < 8; ++blk) {
;             const int ai = blk >> 2, bj = (blk >> 1) & 1, n = blk & 1;
;             if (blk < 7) { int chb_ = chb; asm volatile("" : "+v"(chb_));
;                 const int cidx = (((blk + 1) >> 1) & 1) * DFF + chb_ + 4 * ((blk + 1) & 1);
;                 nw0 = *(const f32x4*)(cw + cidx); nw1 = *(const f32x4*)(cw + NUP + cidx); nw2 = *(const f32x4*)(cw + 2 * NUP + cidx); nbb = *(const f32x4*)(cb + cidx); }
;             asm volatile("" : "+v"(w0), "+v"(w1), "+v"(w2), "+v"(bb));
; #pragma unroll
;             for (int m = 3; m >= 0; --m) {
;                 f32x4 v = acc[ai][bj][m][n]; f32x4 pv = (m > 0) ? acc[ai][bj][m > 0 ? m - 1 : 0][n] : (f32x4){0.f, 0.f, 0.f, 0.f};
;                 asm volatile("" : "+v"(v), "+v"(pv));
;                 f32x4 r;
; #pragma unroll
;                 for (int e = 0; e < 4; ++e) {
;                     const float o1 = dppf<0x121>(0.f, pv[e]), o2 = dppf<0x122>(0.f, pv[e]);
;                     const float p1 = dppf<0x111>(o1, v[e]), p2 = dppf<0x112>(o2, v[e]);
;                     r[e] = w2[e] * v[e] + w1[e] * p1 + w0[e] * p2 + bb[e];
;                 }
;                 asm volatile("" : "+v"(r));
;                 acc[ai][bj][m][n] = r;
;             }
;             w0 = nw0; w1 = nw1; w2 = nw2; bb = nbb;
;         }
	v_mov_b32_dpp v111, v133 row_shr:1 row_mask:0xf bank_mask:0xf
	v_mov_b32_dpp v174, v112 row_ror:2 row_mask:0xf bank_mask:0xf
	v_mov_b32_dpp v175, v113 row_ror:2 row_mask:0xf bank_mask:0xf
	v_pk_mul_f32 v[112:113], v[166:167], v[170:171]
	v_pk_mul_f32 v[110:111], v[168:169], v[110:111]
	v_mov_b32_dpp v172, v130 row_shr:2 row_mask:0xf bank_mask:0xf
	v_mov_b32_dpp v173, v131 row_shr:2 row_mask:0xf bank_mask:0xf
	v_mov_b32_dpp v174, v132 row_shr:2 row_mask:0xf bank_mask:0xf
	v_mov_b32_dpp v175, v133 row_shr:2 row_mask:0xf bank_mask:0xf
	v_pk_fma_f32 v[110:111], v[164:165], v[132:133], v[110:111]
	v_pk_fma_f32 v[112:113], v[162:163], v[130:131], v[112:113]
	v_pk_fma_f32 v[110:111], v[156:157], v[174:175], v[110:111]
	v_pk_fma_f32 v[130:131], v[154:155], v[172:173], v[112:113]
	v_pk_add_f32 v[112:113], v[152:153], v[110:111]
	v_pk_add_f32 v[110:111], v[150:151], v[130:131]
	v_mov_b64_e32 v[132:133], v[60:61]
	v_mov_b64_e32 v[130:131], v[58:59]
	v_mov_b32_e32 v170, v1
	v_mov_b32_e32 v172, v1
	v_mov_b32_e32 v171, v1
	v_mov_b32_e32 v173, v1
	v_mov_b32_dpp v170, v130 row_ror:1 row_mask:0xf bank_mask:0xf
	v_mov_b32_dpp v172, v130 row_ror:2 row_mask:0xf bank_mask:0xf
	v_mov_b32_dpp v171, v131 row_ror:1 row_mask:0xf bank_mask:0xf
	v_mov_b32_dpp v173, v131 row_ror:2 row_mask:0xf bank_mask:0xf
	v_mov_b32_e32 v130, v1
	v_mov_b32_e32 v131, v1
	v_mov_b32_dpp v170, v126 row_shr:1 row_mask:0xf bank_mask:0xf
	v_mov_b32_dpp v130, v132 row_ror:1 row_mask:0xf bank_mask:0xf
	v_mov_b32_dpp v131, v133 row_ror:1 row_mask:0xf bank_mask:0xf
	v_mov_b32_dpp v171, v127 row_shr:1 row_mask:0xf bank_mask:0xf
	v_mov_b32_e32 v174, v1
	v_mov_b32_dpp v130, v128 row_shr:1 row_mask:0xf bank_mask:0xf
	v_mov_b32_e32 v175, v1
	v_mov_b32_dpp v131, v129 row_shr:1 row_mask:0xf bank_mask:0xf
	v_mov_b32_dpp v174, v132 row_ror:2 row_mask:0xf bank_mask:0xf
	v_mov_b32_dpp v175, v133 row_ror:2 row_mask:0xf bank_mask:0xf
	v_pk_mul_f32 v[130:131], v[168:169], v[130:131]
	v_pk_mul_f32 v[132:133], v[166:167], v[170:171]
	v_mov_b32_dpp v172, v126 row_shr:2 row_mask:0xf bank_mask:0xf
	v_mov_b32_dpp v173, v127 row_shr:2 row_mask:0xf bank_mask:0xf
	v_mov_b32_dpp v174, v128 row_shr:2 row_mask:0xf bank_mask:0xf
	v_mov_b32_dpp v175, v129 row_shr:2 row_mask:0xf bank_mask:0xf
	v_pk_fma_f32 v[128:129], v[164:165], v[128:129], v[130:131]
	v_pk_fma_f32 v[126:127], v[162:163], v[126:127], v[132:133]
	v_pk_fma_f32 v[128:129], v[156:157], v[174:175], v[128:129]
	v_pk_fma_f32 v[126:127], v[154:155], v[172:173], v[126:127]
	v_mov_b64_e32 v[132:133], s[2:3]
	v_pk_add_f32 v[128:129], v[152:153], v[128:129]
	v_pk_add_f32 v[126:127], v[150:151], v[126:127]
	v_mov_b64_e32 v[130:131], s[0:1]
	v_mov_b32_e32 v170, v1
	v_mov_b32_e32 v172, v1
	v_mov_b32_e32 v171, v1
	v_mov_b32_e32 v173, v1
	v_mov_b32_dpp v170, v130 row_ror:1 row_mask:0xf bank_mask:0xf
	v_mov_b32_dpp v172, v130 row_ror:2 row_mask:0xf bank_mask:0xf
	v_mov_b32_dpp v171, v131 row_ror:1 row_mask:0xf bank_mask:0xf
	v_mov_b32_dpp v173, v131 row_ror:2 row_mask:0xf bank_mask:0xf
	v_mov_b32_e32 v130, v1
	v_mov_b32_e32 v131, v1
	v_mov_b32_dpp v170, v58 row_shr:1 row_mask:0xf bank_mask:0xf
	v_mov_b32_dpp v130, v132 row_ror:1 row_mask:0xf bank_mask:0xf
	v_mov_b32_dpp v131, v133 row_ror:1 row_mask:0xf bank_mask:0xf
	v_mov_b32_dpp v171, v59 row_shr:1 row_mask:0xf bank_mask:0xf
	v_mov_b32_e32 v174, v1
	v_mov_b32_dpp v130, v60 row_shr:1 row_mask:0xf bank_mask:0xf
	v_mov_b32_e32 v175, v1
	v_mov_b32_dpp v131, v61 row_shr:1 row_mask:0xf bank_mask:0xf
	v_mov_b32_dpp v174, v132 row_ror:2 row_mask:0xf bank_mask:0xf
	v_mov_b32_dpp v175, v133 row_ror:2 row_mask:0xf bank_mask:0xf
	v_pk_mul_f32 v[130:131], v[168:169], v[130:131]
	v_pk_mul_f32 v[132:133], v[166:167], v[170:171]
	v_mov_b32_dpp v172, v58 row_shr:2 row_mask:0xf bank_mask:0xf
	v_mov_b32_dpp v173, v59 row_shr:2 row_mask:0xf bank_mask:0xf
	v_mov_b32_dpp v174, v60 row_shr:2 row_mask:0xf bank_mask:0xf
	v_mov_b32_dpp v175, v61 row_shr:2 row_mask:0xf bank_mask:0xf
	v_pk_fma_f32 v[60:61], v[164:165], v[60:61], v[130:131]
	v_pk_fma_f32 v[58:59], v[162:163], v[58:59], v[132:133]
	v_pk_fma_f32 v[60:61], v[156:157], v[174:175], v[60:61]
	v_pk_fma_f32 v[58:59], v[154:155], v[172:173], v[58:59]
	v_pk_add_f32 v[132:133], v[152:153], v[60:61]
	v_pk_add_f32 v[130:131], v[150:151], v[58:59]
	v_mov_b32_e32 v58, v214
	v_mov_b32_e32 v170, v1
	v_add_u32_e32 v60, 4, v58
	v_ashrrev_i32_e32 v61, 31, v60
	v_ashrrev_i32_e32 v59, 31, v58
	v_lshlrev_b64 v[58:59], 2, v[58:59]
	v_lshlrev_b64 v[60:61], 2, v[60:61]
	v_lshl_add_u64 v[162:163], s[36:37], 0, v[58:59]
	v_lshl_add_u64 v[150:151], s[52:53], 0, v[60:61]
	v_lshl_add_u64 v[60:61], s[54:55], 0, v[60:61]
	v_lshl_add_u64 v[58:59], s[48:49], 0, v[58:59]
	global_load_dwordx4 v[154:157], v[60:61], off
	global_load_dwordx4 v[166:169], v[150:151], off
	s_nop 0
	global_load_dwordx4 v[150:153], v[58:59], off offset:16
	s_nop 0
	global_load_dwordx4 v[162:165], v[162:163], off offset:16
	v_mov_b64_e32 v[58:59], v[114:115]
	v_mov_b64_e32 v[60:61], v[116:117]
	s_waitcnt vmcnt(4)
; template <int CTRL> __device__ __forceinline__ float dppf(float old, float src) { return __int_as_float(__builtin_amdgcn_update_dpp(__float_as_int(old), __float_as_int(src), CTRL, 0xf, 0xf, false)); }
;     __device__ __forceinline__ void operator()(f32x4 (&acc)[2][2][4][2], const Unit& u, int wr, int wc, int fr, int fq) const {
;     ...
;         f32x4 w0, w1, w2, bb, nw0, nw1, nw2, nbb;
;         { w0 = *(const f32x4*)(cw + chb); w1 = *(const f32x4*)(cw + NUP + chb); w2 = *(const f32x4*)(cw + 2 * NUP + chb); bb = *(const f32x4*)(cb + chb); nw0 = w0; nw1 = w1; nw2 = w2; nbb = bb; }
; #pragma unroll
;         for (int blk = 0; blk < 8; ++blk) {
;             const int ai = blk >> 2, bj = (blk >> 1) & 1, n = blk & 1;
;             if (blk < 7) { int chb_ = chb; asm volatile("" : "+v"(chb_));
;                 const int cidx = (((blk + 1) >> 1) & 1) * DFF + chb_ + 4 * ((blk + 1) & 1);
;                 nw0 = *(const f32x4*)(cw + cidx); nw1 = *(const f32x4*)(cw + NUP + cidx); nw2 = *(const f32x4*)(cw + 2 * NUP + cidx); nbb = *(const f32x4*)(cb + cidx); }
;             asm volatile("" : "+v"(w0), "+v"(w1), "+v"(w2), "+v"(bb));
; #pragma unroll
;             for (int m = 3; m >= 0; --m) {
;                 f32x4 v = acc[ai][bj][m][n]; f32x4 pv = (m > 0) ? acc[ai][bj][m > 0 ? m - 1 : 0][n] : (f32x4){0.f, 0.f, 0.f, 0.f};
;                 asm volatile("" : "+v"(v), "+v"(pv));
;                 f32x4 r;
; #pragma unroll
;                 for (int e = 0; e < 4; ++e) {
;                     const float o1 = dppf<0x121>(0.f, pv[e]), o2 = dppf<0x122>(0.f, pv[e]);
;                     const float p1 = dppf<0x111>(o1, v[e]), p2 = dppf<0x112>(o2, v[e]);
;                     r[e] = w2[e] * v[e] + w1[e] * p1 + w0[e] * p2 + bb[e];
;                 }
;                 asm volatile("" : "+v"(r));
;                 acc[ai][bj][m][n] = r;
;             }
;             w0 = nw0; w1 = nw1; w2 = nw2; bb = nbb;
;         }
	v_mov_b32_e32 v172, v1
	v_mov_b32_e32 v171, v1
	v_mov_b32_e32 v173, v1
	v_mov_b32_dpp v170, v58 row_ror:1 row_mask:0xf bank_mask:0xf
	v_mov_b32_dpp v172, v58 row_ror:2 row_mask:0xf bank_mask:0xf
	v_mov_b32_dpp v171, v59 row_ror:1 row_mask:0xf bank_mask:0xf
	v_mov_b32_dpp v173, v59 row_ror:2 row_mask:0xf bank_mask:0xf
	v_mov_b32_e32 v58, v1
	v_mov_b32_e32 v59, v1
	v_mov_b32_dpp v170, v18 row_shr:1 row_mask:0xf bank_mask:0xf
	v_mov_b32_dpp v58, v60 row_ror:1 row_mask:0xf bank_mask:0xf
	v_mov_b32_dpp v59, v61 row_ror:1 row_mask:0xf bank_mask:0xf
	v_mov_b32_dpp v171, v19 row_shr:1 row_mask:0xf bank_mask:0xf
	v_mov_b32_e32 v174, v1
	v_mov_b32_dpp v58, v20 row_shr:1 row_mask:0xf bank_mask:0xf
	v_mov_b32_e32 v175, v1
	v_mov_b32_dpp v59, v21 row_shr:1 row_mask:0xf bank_mask:0xf
	v_mov_b32_dpp v174, v60 row_ror:2 row_mask:0xf bank_mask:0xf
	v_mov_b32_dpp v175, v61 row_ror:2 row_mask:0xf bank_mask:0xf
	v_pk_mul_f32 v[60:61], v[158:159], v[170:171]
	v_pk_mul_f32 v[58:59], v[160:161], v[58:59]
	v_mov_b32_dpp v172, v18 row_shr:2 row_mask:0xf bank_mask:0xf
	v_mov_b32_dpp v173, v19 row_shr:2 row_mask:0xf bank_mask:0xf
	v_mov_b32_dpp v174, v20 row_shr:2 row_mask:0xf bank_mask:0xf
	v_mov_b32_dpp v175, v21 row_shr:2 row_mask:0xf bank_mask:0xf
	v_pk_fma_f32 v[20:21], v[148:149], v[20:21], v[58:59]
	v_pk_fma_f32 v[18:19], v[146:147], v[18:19], v[60:61]
	v_pk_fma_f32 v[20:21], v[144:145], v[174:175], v[20:21]
	v_pk_fma_f32 v[18:19], v[142:143], v[172:173], v[18:19]
	v_mov_b64_e32 v[58:59], v[94:95]
	v_pk_add_f32 v[20:21], v[140:141], v[20:21]
	v_pk_add_f32 v[18:19], v[138:139], v[18:19]
	v_mov_b64_e32 v[60:61], v[96:97]
	v_mov_b32_e32 v170, v1
	v_mov_b32_e32 v172, v1
	v_mov_b32_e32 v171, v1
	v_mov_b32_e32 v173, v1
	v_mov_b32_dpp v170, v58 row_ror:1 row_mask:0xf bank_mask:0xf
	v_mov_b32_dpp v172, v58 row_ror:2 row_mask:0xf bank_mask:0xf
	v_mov_b32_dpp v171, v59 row_ror:1 row_mask:0xf bank_mask:0xf
	v_mov_b32_dpp v173, v59 row_ror:2 row_mask:0xf bank_mask:0xf
	v_mov_b32_e32 v58, v1
	v_mov_b32_e32 v59, v1
	v_mov_b32_dpp v170, v114 row_shr:1 row_mask:0xf bank_mask:0xf
	v_mov_b32_dpp v58, v60 row_ror:1 row_mask:0xf bank_mask:0xf
	v_mov_b32_dpp v59, v61 row_ror:1 row_mask:0xf bank_mask:0xf
	v_mov_b32_dpp v171, v115 row_shr:1 row_mask:0xf bank_mask:0xf
	v_mov_b32_e32 v174, v1
	v_mov_b32_dpp v58, v116 row_shr:1 row_mask:0xf bank_mask:0xf
	v_mov_b32_e32 v175, v1
	v_mov_b32_dpp v59, v117 row_shr:1 row_mask:0xf bank_mask:0xf
	v_mov_b32_dpp v174, v60 row_ror:2 row_mask:0xf bank_mask:0xf
	v_mov_b32_dpp v175, v61 row_ror:2 row_mask:0xf bank_mask:0xf
	v_pk_mul_f32 v[60:61], v[158:159], v[170:171]
	v_pk_mul_f32 v[58:59], v[160:161], v[58:59]
	v_mov_b32_dpp v172, v114 row_shr:2 row_mask:0xf bank_mask:0xf
	v_mov_b32_dpp v173, v115 row_shr:2 row_mask:0xf bank_mask:0xf
	v_mov_b32_dpp v174, v116 row_shr:2 row_mask:0xf bank_mask:0xf
	v_mov_b32_dpp v175, v117 row_shr:2 row_mask:0xf bank_mask:0xf
	v_pk_fma_f32 v[58:59], v[148:149], v[116:117], v[58:59]
	v_pk_fma_f32 v[60:61], v[146:147], v[114:115], v[60:61]
	v_pk_fma_f32 v[58:59], v[144:145], v[174:175], v[58:59]
	v_pk_fma_f32 v[114:115], v[142:143], v[172:173], v[60:61]
	v_pk_add_f32 v[60:61], v[140:141], v[58:59]
	v_pk_add_f32 v[58:59], v[138:139], v[114:115]
	v_mov_b64_e32 v[116:117], v[40:41]
	v_mov_b64_e32 v[114:115], v[38:39]
	v_mov_b32_e32 v170, v1
	v_mov_b32_e32 v172, v1
	v_mov_b32_e32 v171, v1
	v_mov_b32_e32 v173, v1
	v_mov_b32_dpp v170, v114 row_ror:1 row_mask:0xf bank_mask:0xf
	v_mov_b32_dpp v172, v114 row_ror:2 row_mask:0xf bank_mask:0xf
	v_mov_b32_dpp v171, v115 row_ror:1 row_mask:0xf bank_mask:0xf
	v_mov_b32_dpp v173, v115 row_ror:2 row_mask:0xf bank_mask:0xf
	v_mov_b32_e32 v114, v1
	v_mov_b32_e32 v115, v1
	v_mov_b32_dpp v170, v94 row_shr:1 row_mask:0xf bank_mask:0xf
	v_mov_b32_dpp v114, v116 row_ror:1 row_mask:0xf bank_mask:0xf
	v_mov_b32_dpp v115, v117 row_ror:1 row_mask:0xf bank_mask:0xf
	v_mov_b32_dpp v171, v95 row_shr:1 row_mask:0xf bank_mask:0xf
	v_mov_b32_e32 v174, v1
	v_mov_b32_dpp v114, v96 row_shr:1 row_mask:0xf bank_mask:0xf
	v_mov_b32_e32 v175, v1
	v_mov_b32_dpp v115, v97 row_shr:1 row_mask:0xf bank_mask:0xf
	v_mov_b32_dpp v174, v116 row_ror:2 row_mask:0xf bank_mask:0xf
	v_mov_b32_dpp v175, v117 row_ror:2 row_mask:0xf bank_mask:0xf
	v_pk_mul_f32 v[116:117], v[158:159], v[170:171]
	v_pk_mul_f32 v[114:115], v[160:161], v[114:115]
	v_mov_b32_dpp v172, v94 row_shr:2 row_mask:0xf bank_mask:0xf
	v_mov_b32_dpp v173, v95 row_shr:2 row_mask:0xf bank_mask:0xf
	v_mov_b32_dpp v174, v96 row_shr:2 row_mask:0xf bank_mask:0xf
	v_mov_b32_dpp v175, v97 row_shr:2 row_mask:0xf bank_mask:0xf
	v_pk_fma_f32 v[96:97], v[148:149], v[96:97], v[114:115]
	v_pk_fma_f32 v[94:95], v[146:147], v[94:95], v[116:117]
	v_pk_fma_f32 v[96:97], v[144:145], v[174:175], v[96:97]
	v_pk_fma_f32 v[94:95], v[142:143], v[172:173], v[94:95]
	v_mov_b64_e32 v[116:117], s[2:3]
	v_pk_add_f32 v[96:97], v[140:141], v[96:97]
	v_pk_add_f32 v[94:95], v[138:139], v[94:95]
	v_mov_b64_e32 v[114:115], s[0:1]
	v_mov_b32_e32 v170, v1
	v_mov_b32_e32 v172, v1
	v_mov_b32_e32 v171, v1
	v_mov_b32_e32 v173, v1
	v_mov_b32_dpp v170, v114 row_ror:1 row_mask:0xf bank_mask:0xf
	v_mov_b32_dpp v172, v114 row_ror:2 row_mask:0xf bank_mask:0xf
	v_mov_b32_dpp v171, v115 row_ror:1 row_mask:0xf bank_mask:0xf
	v_mov_b32_dpp v173, v115 row_ror:2 row_mask:0xf bank_mask:0xf
	v_mov_b32_e32 v114, v1
	v_mov_b32_e32 v115, v1
	v_mov_b32_dpp v170, v38 row_shr:1 row_mask:0xf bank_mask:0xf
	v_mov_b32_dpp v114, v116 row_ror:1 row_mask:0xf bank_mask:0xf
	v_mov_b32_dpp v115, v117 row_ror:1 row_mask:0xf bank_mask:0xf
	v_mov_b32_dpp v171, v39 row_shr:1 row_mask:0xf bank_mask:0xf
	v_mov_b32_e32 v174, v1
; template <int CTRL> __device__ __forceinline__ float dppf(float old, float src) { return __int_as_float(__builtin_amdgcn_update_dpp(__float_as_int(old), __float_as_int(src), CTRL, 0xf, 0xf, false)); }
;     __device__ __forceinline__ void operator()(f32x4 (&acc)[2][2][4][2], const Unit& u, int wr, int wc, int fr, int fq) const {
;     ...
;         f32x4 w0, w1, w2, bb, nw0, nw1, nw2, nbb;
;         { w0 = *(const f32x4*)(cw + chb); w1 = *(const f32x4*)(cw + NUP + chb); w2 = *(const f32x4*)(cw + 2 * NUP + chb); bb = *(const f32x4*)(cb + chb); nw0 = w0; nw1 = w1; nw2 = w2; nbb = bb; }
; #pragma unroll
;         for (int blk = 0; blk < 8; ++blk) {
;             const int ai = blk >> 2, bj = (blk >> 1) & 1, n = blk & 1;
;             if (blk < 7) { int chb_ = chb; asm volatile("" : "+v"(chb_));
;                 const int cidx = (((blk + 1) >> 1) & 1) * DFF + chb_ + 4 * ((blk + 1) & 1);
;                 nw0 = *(const f32x4*)(cw + cidx); nw1 = *(const f32x4*)(cw + NUP + cidx); nw2 = *(const f32x4*)(cw + 2 * NUP + cidx); nbb = *(const f32x4*)(cb + cidx); }
;             asm volatile("" : "+v"(w0), "+v"(w1), "+v"(w2), "+v"(bb));
; #pragma unroll
;             for (int m = 3; m >= 0; --m) {
;                 f32x4 v = acc[ai][bj][m][n]; f32x4 pv = (m > 0) ? acc[ai][bj][m > 0 ? m - 1 : 0][n] : (f32x4){0.f, 0.f, 0.f, 0.f};
;                 asm volatile("" : "+v"(v), "+v"(pv));
;                 f32x4 r;
; #pragma unroll
;                 for (int e = 0; e < 4; ++e) {
;                     const float o1 = dppf<0x121>(0.f, pv[e]), o2 = dppf<0x122>(0.f, pv[e]);
;                     const float p1 = dppf<0x111>(o1, v[e]), p2 = dppf<0x112>(o2, v[e]);
;                     r[e] = w2[e] * v[e] + w1[e] * p1 + w0[e] * p2 + bb[e];
;                 }
;                 asm volatile("" : "+v"(r));
;                 acc[ai][bj][m][n] = r;
;             }
;             w0 = nw0; w1 = nw1; w2 = nw2; bb = nbb;
;         }
	v_mov_b32_dpp v114, v40 row_shr:1 row_mask:0xf bank_mask:0xf
	v_mov_b32_e32 v175, v1
	v_mov_b32_dpp v115, v41 row_shr:1 row_mask:0xf bank_mask:0xf
	v_mov_b32_dpp v174, v116 row_ror:2 row_mask:0xf bank_mask:0xf
	v_mov_b32_dpp v175, v117 row_ror:2 row_mask:0xf bank_mask:0xf
	v_pk_mul_f32 v[114:115], v[160:161], v[114:115]
	v_pk_mul_f32 v[116:117], v[158:159], v[170:171]
	v_mov_b32_dpp v172, v38 row_shr:2 row_mask:0xf bank_mask:0xf
	v_mov_b32_dpp v173, v39 row_shr:2 row_mask:0xf bank_mask:0xf
	v_mov_b32_dpp v174, v40 row_shr:2 row_mask:0xf bank_mask:0xf
	v_mov_b32_dpp v175, v41 row_shr:2 row_mask:0xf bank_mask:0xf
	v_pk_fma_f32 v[40:41], v[148:149], v[40:41], v[114:115]
	v_pk_fma_f32 v[38:39], v[146:147], v[38:39], v[116:117]
	v_pk_fma_f32 v[40:41], v[144:145], v[174:175], v[40:41]
	v_pk_fma_f32 v[38:39], v[142:143], v[172:173], v[38:39]
	v_pk_add_f32 v[116:117], v[140:141], v[40:41]
	v_pk_add_f32 v[114:115], v[138:139], v[38:39]
	v_mov_b32_e32 v38, v214
	v_mov_b32_e32 v170, v1
	v_add_u32_e32 v38, 0x1600, v38
	v_ashrrev_i32_e32 v39, 31, v38
	v_lshlrev_b64 v[38:39], 2, v[38:39]
	v_lshl_add_u64 v[40:41], s[36:37], 0, v[38:39]
	v_lshl_add_u64 v[142:143], s[52:53], 0, v[38:39]
	v_lshl_add_u64 v[144:145], s[54:55], 0, v[38:39]
	v_lshl_add_u64 v[38:39], s[48:49], 0, v[38:39]
	global_load_dwordx4 v[138:141], v[38:39], off
	global_load_dwordx4 v[146:149], v[144:145], off
	global_load_dwordx4 v[158:161], v[142:143], off
	s_nop 0
	global_load_dwordx4 v[142:145], v[40:41], off
	v_mov_b64_e32 v[38:39], v[90:91]
	v_mov_b64_e32 v[40:41], v[92:93]
	s_waitcnt vmcnt(4)
	v_mov_b32_e32 v172, v1
	v_mov_b32_e32 v171, v1
	v_mov_b32_e32 v173, v1
	v_mov_b32_dpp v170, v38 row_ror:1 row_mask:0xf bank_mask:0xf
	v_mov_b32_dpp v172, v38 row_ror:2 row_mask:0xf bank_mask:0xf
	v_mov_b32_dpp v171, v39 row_ror:1 row_mask:0xf bank_mask:0xf
	v_mov_b32_dpp v173, v39 row_ror:2 row_mask:0xf bank_mask:0xf
	v_mov_b32_e32 v38, v1
	v_mov_b32_e32 v39, v1
	v_mov_b32_dpp v170, v74 row_shr:1 row_mask:0xf bank_mask:0xf
	v_mov_b32_dpp v38, v40 row_ror:1 row_mask:0xf bank_mask:0xf
	v_mov_b32_dpp v39, v41 row_ror:1 row_mask:0xf bank_mask:0xf
	v_mov_b32_dpp v171, v75 row_shr:1 row_mask:0xf bank_mask:0xf
	v_mov_b32_e32 v174, v1
	v_mov_b32_dpp v38, v76 row_shr:1 row_mask:0xf bank_mask:0xf
	v_mov_b32_e32 v175, v1
	v_mov_b32_dpp v39, v77 row_shr:1 row_mask:0xf bank_mask:0xf
	v_mov_b32_dpp v174, v40 row_ror:2 row_mask:0xf bank_mask:0xf
	v_mov_b32_dpp v175, v41 row_ror:2 row_mask:0xf bank_mask:0xf
	v_pk_mul_f32 v[40:41], v[166:167], v[170:171]
	v_pk_mul_f32 v[38:39], v[168:169], v[38:39]
	v_mov_b32_dpp v172, v74 row_shr:2 row_mask:0xf bank_mask:0xf
	v_mov_b32_dpp v173, v75 row_shr:2 row_mask:0xf bank_mask:0xf
	v_mov_b32_dpp v174, v76 row_shr:2 row_mask:0xf bank_mask:0xf
	v_mov_b32_dpp v175, v77 row_shr:2 row_mask:0xf bank_mask:0xf
	v_pk_fma_f32 v[38:39], v[156:157], v[76:77], v[38:39]
	v_pk_fma_f32 v[40:41], v[154:155], v[74:75], v[40:41]
	v_pk_fma_f32 v[38:39], v[164:165], v[174:175], v[38:39]
	v_pk_fma_f32 v[74:75], v[162:163], v[172:173], v[40:41]
	v_pk_add_f32 v[40:41], v[152:153], v[38:39]
	v_pk_add_f32 v[38:39], v[150:151], v[74:75]
	v_mov_b64_e32 v[74:75], v[78:79]
	v_mov_b64_e32 v[76:77], v[80:81]
	v_mov_b32_e32 v170, v1
	v_mov_b32_e32 v172, v1
	v_mov_b32_e32 v171, v1
	v_mov_b32_e32 v173, v1
	v_mov_b32_dpp v170, v74 row_ror:1 row_mask:0xf bank_mask:0xf
	v_mov_b32_dpp v172, v74 row_ror:2 row_mask:0xf bank_mask:0xf
	v_mov_b32_dpp v171, v75 row_ror:1 row_mask:0xf bank_mask:0xf
	v_mov_b32_dpp v173, v75 row_ror:2 row_mask:0xf bank_mask:0xf
	v_mov_b32_e32 v74, v1
	v_mov_b32_e32 v75, v1
	v_mov_b32_dpp v170, v90 row_shr:1 row_mask:0xf bank_mask:0xf
	v_mov_b32_dpp v74, v76 row_ror:1 row_mask:0xf bank_mask:0xf
	v_mov_b32_dpp v75, v77 row_ror:1 row_mask:0xf bank_mask:0xf
	v_mov_b32_dpp v171, v91 row_shr:1 row_mask:0xf bank_mask:0xf
	v_mov_b32_e32 v174, v1
	v_mov_b32_dpp v74, v92 row_shr:1 row_mask:0xf bank_mask:0xf
	v_mov_b32_e32 v175, v1
	v_mov_b32_dpp v75, v93 row_shr:1 row_mask:0xf bank_mask:0xf
	v_mov_b32_dpp v174, v76 row_ror:2 row_mask:0xf bank_mask:0xf
	v_mov_b32_dpp v175, v77 row_ror:2 row_mask:0xf bank_mask:0xf
	v_pk_mul_f32 v[76:77], v[166:167], v[170:171]
	v_pk_mul_f32 v[74:75], v[168:169], v[74:75]
	v_mov_b32_dpp v172, v90 row_shr:2 row_mask:0xf bank_mask:0xf
	v_mov_b32_dpp v173, v91 row_shr:2 row_mask:0xf bank_mask:0xf
	v_mov_b32_dpp v174, v92 row_shr:2 row_mask:0xf bank_mask:0xf
	v_mov_b32_dpp v175, v93 row_shr:2 row_mask:0xf bank_mask:0xf
	v_pk_fma_f32 v[74:75], v[156:157], v[92:93], v[74:75]
	v_pk_fma_f32 v[76:77], v[154:155], v[90:91], v[76:77]
	v_pk_fma_f32 v[74:75], v[164:165], v[174:175], v[74:75]
	v_pk_fma_f32 v[90:91], v[162:163], v[172:173], v[76:77]
	v_pk_add_f32 v[76:77], v[152:153], v[74:75]
	v_pk_add_f32 v[74:75], v[150:151], v[90:91]
	v_mov_b64_e32 v[92:93], v[52:53]
	v_mov_b64_e32 v[90:91], v[50:51]
	v_mov_b32_e32 v170, v1
	v_mov_b32_e32 v172, v1
	v_mov_b32_e32 v171, v1
	v_mov_b32_e32 v173, v1
	v_mov_b32_dpp v170, v90 row_ror:1 row_mask:0xf bank_mask:0xf
	v_mov_b32_dpp v172, v90 row_ror:2 row_mask:0xf bank_mask:0xf
	v_mov_b32_dpp v171, v91 row_ror:1 row_mask:0xf bank_mask:0xf
	v_mov_b32_dpp v173, v91 row_ror:2 row_mask:0xf bank_mask:0xf
	v_mov_b32_e32 v90, v1
	v_mov_b32_e32 v91, v1
	v_mov_b32_dpp v170, v78 row_shr:1 row_mask:0xf bank_mask:0xf
	v_mov_b32_dpp v90, v92 row_ror:1 row_mask:0xf bank_mask:0xf
	v_mov_b32_dpp v91, v93 row_ror:1 row_mask:0xf bank_mask:0xf
	v_mov_b32_dpp v171, v79 row_shr:1 row_mask:0xf bank_mask:0xf
	v_mov_b32_e32 v174, v1
	v_mov_b32_dpp v90, v80 row_shr:1 row_mask:0xf bank_mask:0xf
	v_mov_b32_e32 v175, v1
	v_mov_b32_dpp v91, v81 row_shr:1 row_mask:0xf bank_mask:0xf
; template <int CTRL> __device__ __forceinline__ float dppf(float old, float src) { return __int_as_float(__builtin_amdgcn_update_dpp(__float_as_int(old), __float_as_int(src), CTRL, 0xf, 0xf, false)); }
;     __device__ __forceinline__ void operator()(f32x4 (&acc)[2][2][4][2], const Unit& u, int wr, int wc, int fr, int fq) const {
;     ...
;         f32x4 w0, w1, w2, bb, nw0, nw1, nw2, nbb;
;         { w0 = *(const f32x4*)(cw + chb); w1 = *(const f32x4*)(cw + NUP + chb); w2 = *(const f32x4*)(cw + 2 * NUP + chb); bb = *(const f32x4*)(cb + chb); nw0 = w0; nw1 = w1; nw2 = w2; nbb = bb; }
; #pragma unroll
;         for (int blk = 0; blk < 8; ++blk) {
;             const int ai = blk >> 2, bj = (blk >> 1) & 1, n = blk & 1;
;             if (blk < 7) { int chb_ = chb; asm volatile("" : "+v"(chb_));
;                 const int cidx = (((blk + 1) >> 1) & 1) * DFF + chb_ + 4 * ((blk + 1) & 1);
;                 nw0 = *(const f32x4*)(cw + cidx); nw1 = *(const f32x4*)(cw + NUP + cidx); nw2 = *(const f32x4*)(cw + 2 * NUP + cidx); nbb = *(const f32x4*)(cb + cidx); }
;             asm volatile("" : "+v"(w0), "+v"(w1), "+v"(w2), "+v"(bb));
; #pragma unroll
;             for (int m = 3; m >= 0; --m) {
;                 f32x4 v = acc[ai][bj][m][n]; f32x4 pv = (m > 0) ? acc[ai][bj][m > 0 ? m - 1 : 0][n] : (f32x4){0.f, 0.f, 0.f, 0.f};
;                 asm volatile("" : "+v"(v), "+v"(pv));
;                 f32x4 r;
; #pragma unroll
;                 for (int e = 0; e < 4; ++e) {
;                     const float o1 = dppf<0x121>(0.f, pv[e]), o2 = dppf<0x122>(0.f, pv[e]);
;                     const float p1 = dppf<0x111>(o1, v[e]), p2 = dppf<0x112>(o2, v[e]);
;                     r[e] = w2[e] * v[e] + w1[e] * p1 + w0[e] * p2 + bb[e];
;                 }
;                 asm volatile("" : "+v"(r));
;                 acc[ai][bj][m][n] = r;
;             }
;             w0 = nw0; w1 = nw1; w2 = nw2; bb = nbb;
;         }
	v_mov_b32_dpp v174, v92 row_ror:2 row_mask:0xf bank_mask:0xf
	v_mov_b32_dpp v175, v93 row_ror:2 row_mask:0xf bank_mask:0xf
	v_pk_mul_f32 v[92:93], v[166:167], v[170:171]
	v_pk_mul_f32 v[90:91], v[168:169], v[90:91]
	v_mov_b32_dpp v172, v78 row_shr:2 row_mask:0xf bank_mask:0xf
	v_mov_b32_dpp v173, v79 row_shr:2 row_mask:0xf bank_mask:0xf
	v_mov_b32_dpp v174, v80 row_shr:2 row_mask:0xf bank_mask:0xf
	v_mov_b32_dpp v175, v81 row_shr:2 row_mask:0xf bank_mask:0xf
	v_pk_fma_f32 v[80:81], v[156:157], v[80:81], v[90:91]
	v_pk_fma_f32 v[78:79], v[154:155], v[78:79], v[92:93]
	v_pk_fma_f32 v[80:81], v[164:165], v[174:175], v[80:81]
	v_pk_fma_f32 v[78:79], v[162:163], v[172:173], v[78:79]
	v_mov_b64_e32 v[92:93], s[2:3]
	v_pk_add_f32 v[80:81], v[152:153], v[80:81]
	v_pk_add_f32 v[78:79], v[150:151], v[78:79]
	v_mov_b64_e32 v[90:91], s[0:1]
	v_mov_b32_e32 v170, v1
	v_mov_b32_e32 v172, v1
	v_mov_b32_e32 v171, v1
	v_mov_b32_e32 v173, v1
	v_mov_b32_dpp v170, v90 row_ror:1 row_mask:0xf bank_mask:0xf
	v_mov_b32_dpp v172, v90 row_ror:2 row_mask:0xf bank_mask:0xf
	v_mov_b32_dpp v171, v91 row_ror:1 row_mask:0xf bank_mask:0xf
	v_mov_b32_dpp v173, v91 row_ror:2 row_mask:0xf bank_mask:0xf
	v_mov_b32_e32 v90, v1
	v_mov_b32_e32 v91, v1
	v_mov_b32_dpp v170, v50 row_shr:1 row_mask:0xf bank_mask:0xf
	v_mov_b32_dpp v90, v92 row_ror:1 row_mask:0xf bank_mask:0xf
	v_mov_b32_dpp v91, v93 row_ror:1 row_mask:0xf bank_mask:0xf
	v_mov_b32_dpp v171, v51 row_shr:1 row_mask:0xf bank_mask:0xf
	v_mov_b32_e32 v174, v1
	v_mov_b32_dpp v90, v52 row_shr:1 row_mask:0xf bank_mask:0xf
	v_mov_b32_e32 v175, v1
	v_mov_b32_dpp v91, v53 row_shr:1 row_mask:0xf bank_mask:0xf
	v_mov_b32_dpp v174, v92 row_ror:2 row_mask:0xf bank_mask:0xf
	v_mov_b32_dpp v175, v93 row_ror:2 row_mask:0xf bank_mask:0xf
	v_pk_mul_f32 v[92:93], v[166:167], v[170:171]
	v_pk_mul_f32 v[90:91], v[168:169], v[90:91]
	v_mov_b32_dpp v172, v50 row_shr:2 row_mask:0xf bank_mask:0xf
	v_mov_b32_dpp v173, v51 row_shr:2 row_mask:0xf bank_mask:0xf
	v_mov_b32_dpp v174, v52 row_shr:2 row_mask:0xf bank_mask:0xf
	v_mov_b32_dpp v175, v53 row_shr:2 row_mask:0xf bank_mask:0xf
	v_pk_fma_f32 v[52:53], v[156:157], v[52:53], v[90:91]
	v_pk_fma_f32 v[50:51], v[154:155], v[50:51], v[92:93]
	v_pk_fma_f32 v[52:53], v[164:165], v[174:175], v[52:53]
	v_pk_fma_f32 v[50:51], v[162:163], v[172:173], v[50:51]
	v_pk_add_f32 v[92:93], v[152:153], v[52:53]
	v_pk_add_f32 v[90:91], v[150:151], v[50:51]
	v_mov_b32_e32 v50, v214
	v_mov_b32_e32 v170, v1
	v_add_u32_e32 v50, 0x1604, v50
	v_ashrrev_i32_e32 v51, 31, v50
	v_lshlrev_b64 v[50:51], 2, v[50:51]
	v_lshl_add_u64 v[52:53], s[36:37], 0, v[50:51]
	v_lshl_add_u64 v[154:155], s[52:53], 0, v[50:51]
	v_lshl_add_u64 v[156:157], s[54:55], 0, v[50:51]
	v_lshl_add_u64 v[50:51], s[48:49], 0, v[50:51]
	global_load_dwordx4 v[150:153], v[50:51], off
	global_load_dwordx4 v[162:165], v[156:157], off
	global_load_dwordx4 v[166:169], v[154:155], off
	s_nop 0
	global_load_dwordx4 v[154:157], v[52:53], off
	v_mov_b64_e32 v[50:51], v[62:63]
	v_mov_b64_e32 v[52:53], v[64:65]
	s_waitcnt vmcnt(4)
	v_mov_b32_e32 v172, v1
	v_mov_b32_e32 v171, v1
	v_mov_b32_e32 v173, v1
	v_mov_b32_dpp v170, v50 row_ror:1 row_mask:0xf bank_mask:0xf
	v_mov_b32_dpp v172, v50 row_ror:2 row_mask:0xf bank_mask:0xf
	v_mov_b32_dpp v171, v51 row_ror:1 row_mask:0xf bank_mask:0xf
	v_mov_b32_dpp v173, v51 row_ror:2 row_mask:0xf bank_mask:0xf
	v_mov_b32_e32 v50, v1
	v_mov_b32_e32 v51, v1
	v_mov_b32_dpp v170, v46 row_shr:1 row_mask:0xf bank_mask:0xf
	v_mov_b32_dpp v50, v52 row_ror:1 row_mask:0xf bank_mask:0xf
	v_mov_b32_dpp v51, v53 row_ror:1 row_mask:0xf bank_mask:0xf
	v_mov_b32_dpp v171, v47 row_shr:1 row_mask:0xf bank_mask:0xf
	v_mov_b32_e32 v174, v1
	v_mov_b32_dpp v50, v48 row_shr:1 row_mask:0xf bank_mask:0xf
	v_mov_b32_e32 v175, v1
	v_mov_b32_dpp v51, v49 row_shr:1 row_mask:0xf bank_mask:0xf
	v_mov_b32_dpp v174, v52 row_ror:2 row_mask:0xf bank_mask:0xf
	v_mov_b32_dpp v175, v53 row_ror:2 row_mask:0xf bank_mask:0xf
	v_pk_mul_f32 v[50:51], v[160:161], v[50:51]
	v_pk_mul_f32 v[52:53], v[158:159], v[170:171]
	v_mov_b32_dpp v172, v46 row_shr:2 row_mask:0xf bank_mask:0xf
	v_mov_b32_dpp v173, v47 row_shr:2 row_mask:0xf bank_mask:0xf
	v_mov_b32_dpp v174, v48 row_shr:2 row_mask:0xf bank_mask:0xf
	v_mov_b32_dpp v175, v49 row_shr:2 row_mask:0xf bank_mask:0xf
	v_pk_fma_f32 v[48:49], v[148:149], v[48:49], v[50:51]
	v_pk_fma_f32 v[46:47], v[146:147], v[46:47], v[52:53]
	v_pk_fma_f32 v[48:49], v[144:145], v[174:175], v[48:49]
	v_pk_fma_f32 v[46:47], v[142:143], v[172:173], v[46:47]
	v_mov_b64_e32 v[52:53], v[44:45]
	v_pk_add_f32 v[48:49], v[140:141], v[48:49]
	v_pk_add_f32 v[46:47], v[138:139], v[46:47]
	v_mov_b64_e32 v[50:51], v[42:43]
	v_mov_b32_e32 v170, v1
	v_mov_b32_e32 v172, v1
	v_mov_b32_e32 v171, v1
	v_mov_b32_e32 v173, v1
	v_mov_b32_dpp v170, v50 row_ror:1 row_mask:0xf bank_mask:0xf
	v_mov_b32_dpp v172, v50 row_ror:2 row_mask:0xf bank_mask:0xf
	v_mov_b32_dpp v171, v51 row_ror:1 row_mask:0xf bank_mask:0xf
	v_mov_b32_dpp v173, v51 row_ror:2 row_mask:0xf bank_mask:0xf
	v_mov_b32_e32 v50, v1
	v_mov_b32_e32 v51, v1
	v_mov_b32_dpp v170, v62 row_shr:1 row_mask:0xf bank_mask:0xf
	v_mov_b32_dpp v50, v52 row_ror:1 row_mask:0xf bank_mask:0xf
	v_mov_b32_dpp v51, v53 row_ror:1 row_mask:0xf bank_mask:0xf
	v_mov_b32_dpp v171, v63 row_shr:1 row_mask:0xf bank_mask:0xf
	v_mov_b32_e32 v174, v1
	v_mov_b32_dpp v50, v64 row_shr:1 row_mask:0xf bank_mask:0xf
	v_mov_b32_e32 v175, v1
	v_mov_b32_dpp v51, v65 row_shr:1 row_mask:0xf bank_mask:0xf
	v_mov_b32_dpp v174, v52 row_ror:2 row_mask:0xf bank_mask:0xf
	v_mov_b32_dpp v175, v53 row_ror:2 row_mask:0xf bank_mask:0xf
; template <int CTRL> __device__ __forceinline__ float dppf(float old, float src) { return __int_as_float(__builtin_amdgcn_update_dpp(__float_as_int(old), __float_as_int(src), CTRL, 0xf, 0xf, false)); }
;     __device__ __forceinline__ void operator()(f32x4 (&acc)[2][2][4][2], const Unit& u, int wr, int wc, int fr, int fq) const {
;     ...
;         f32x4 w0, w1, w2, bb, nw0, nw1, nw2, nbb;
;         { w0 = *(const f32x4*)(cw + chb); w1 = *(const f32x4*)(cw + NUP + chb); w2 = *(const f32x4*)(cw + 2 * NUP + chb); bb = *(const f32x4*)(cb + chb); nw0 = w0; nw1 = w1; nw2 = w2; nbb = bb; }
; #pragma unroll
;         for (int blk = 0; blk < 8; ++blk) {
;             const int ai = blk >> 2, bj = (blk >> 1) & 1, n = blk & 1;
;             if (blk < 7) { int chb_ = chb; asm volatile("" : "+v"(chb_));
;                 const int cidx = (((blk + 1) >> 1) & 1) * DFF + chb_ + 4 * ((blk + 1) & 1);
;                 nw0 = *(const f32x4*)(cw + cidx); nw1 = *(const f32x4*)(cw + NUP + cidx); nw2 = *(const f32x4*)(cw + 2 * NUP + cidx); nbb = *(const f32x4*)(cb + cidx); }
;             asm volatile("" : "+v"(w0), "+v"(w1), "+v"(w2), "+v"(bb));
; #pragma unroll
;             for (int m = 3; m >= 0; --m) {
;                 f32x4 v = acc[ai][bj][m][n]; f32x4 pv = (m > 0) ? acc[ai][bj][m > 0 ? m - 1 : 0][n] : (f32x4){0.f, 0.f, 0.f, 0.f};
;                 asm volatile("" : "+v"(v), "+v"(pv));
;                 f32x4 r;
; #pragma unroll
;                 for (int e = 0; e < 4; ++e) {
;                     const float o1 = dppf<0x121>(0.f, pv[e]), o2 = dppf<0x122>(0.f, pv[e]);
;                     const float p1 = dppf<0x111>(o1, v[e]), p2 = dppf<0x112>(o2, v[e]);
;                     r[e] = w2[e] * v[e] + w1[e] * p1 + w0[e] * p2 + bb[e];
;                 }
;                 asm volatile("" : "+v"(r));
;                 acc[ai][bj][m][n] = r;
;             }
;             w0 = nw0; w1 = nw1; w2 = nw2; bb = nbb;
;         }
	v_pk_mul_f32 v[52:53], v[158:159], v[170:171]
	v_pk_mul_f32 v[50:51], v[160:161], v[50:51]
	v_mov_b32_dpp v172, v62 row_shr:2 row_mask:0xf bank_mask:0xf
	v_mov_b32_dpp v173, v63 row_shr:2 row_mask:0xf bank_mask:0xf
	v_mov_b32_dpp v174, v64 row_shr:2 row_mask:0xf bank_mask:0xf
	v_mov_b32_dpp v175, v65 row_shr:2 row_mask:0xf bank_mask:0xf
	v_pk_fma_f32 v[50:51], v[148:149], v[64:65], v[50:51]
	v_pk_fma_f32 v[52:53], v[146:147], v[62:63], v[52:53]
	v_pk_fma_f32 v[50:51], v[144:145], v[174:175], v[50:51]
	v_pk_fma_f32 v[62:63], v[142:143], v[172:173], v[52:53]
	v_pk_add_f32 v[52:53], v[140:141], v[50:51]
	v_pk_add_f32 v[50:51], v[138:139], v[62:63]
	v_mov_b64_e32 v[64:65], v[24:25]
	v_mov_b64_e32 v[62:63], v[22:23]
	v_mov_b32_e32 v170, v1
	v_mov_b32_e32 v172, v1
	v_mov_b32_e32 v171, v1
	v_mov_b32_e32 v173, v1
	v_mov_b32_dpp v170, v62 row_ror:1 row_mask:0xf bank_mask:0xf
	v_mov_b32_dpp v172, v62 row_ror:2 row_mask:0xf bank_mask:0xf
	v_mov_b32_dpp v171, v63 row_ror:1 row_mask:0xf bank_mask:0xf
	v_mov_b32_dpp v173, v63 row_ror:2 row_mask:0xf bank_mask:0xf
	v_mov_b32_e32 v62, v1
	v_mov_b32_e32 v63, v1
	v_mov_b32_dpp v170, v42 row_shr:1 row_mask:0xf bank_mask:0xf
	v_mov_b32_dpp v62, v64 row_ror:1 row_mask:0xf bank_mask:0xf
	v_mov_b32_dpp v63, v65 row_ror:1 row_mask:0xf bank_mask:0xf
	v_mov_b32_dpp v171, v43 row_shr:1 row_mask:0xf bank_mask:0xf
	v_mov_b32_e32 v174, v1
	v_mov_b32_dpp v62, v44 row_shr:1 row_mask:0xf bank_mask:0xf
	v_mov_b32_e32 v175, v1
	v_mov_b32_dpp v63, v45 row_shr:1 row_mask:0xf bank_mask:0xf
	v_mov_b32_dpp v174, v64 row_ror:2 row_mask:0xf bank_mask:0xf
	v_mov_b32_dpp v175, v65 row_ror:2 row_mask:0xf bank_mask:0xf
	v_pk_mul_f32 v[62:63], v[160:161], v[62:63]
	v_pk_mul_f32 v[64:65], v[158:159], v[170:171]
	v_mov_b32_dpp v172, v42 row_shr:2 row_mask:0xf bank_mask:0xf
	v_mov_b32_dpp v173, v43 row_shr:2 row_mask:0xf bank_mask:0xf
	v_mov_b32_dpp v174, v44 row_shr:2 row_mask:0xf bank_mask:0xf
	v_mov_b32_dpp v175, v45 row_shr:2 row_mask:0xf bank_mask:0xf
	v_pk_fma_f32 v[44:45], v[148:149], v[44:45], v[62:63]
	v_pk_fma_f32 v[42:43], v[146:147], v[42:43], v[64:65]
	v_pk_fma_f32 v[44:45], v[144:145], v[174:175], v[44:45]
	v_pk_fma_f32 v[42:43], v[142:143], v[172:173], v[42:43]
	v_mov_b64_e32 v[64:65], s[2:3]
	v_pk_add_f32 v[44:45], v[140:141], v[44:45]
	v_pk_add_f32 v[42:43], v[138:139], v[42:43]
	v_mov_b64_e32 v[62:63], s[0:1]
	v_mov_b32_e32 v170, v1
	v_mov_b32_e32 v172, v1
	v_mov_b32_e32 v171, v1
	v_mov_b32_e32 v173, v1
	v_mov_b32_dpp v170, v62 row_ror:1 row_mask:0xf bank_mask:0xf
	v_mov_b32_dpp v172, v62 row_ror:2 row_mask:0xf bank_mask:0xf
	v_mov_b32_dpp v171, v63 row_ror:1 row_mask:0xf bank_mask:0xf
	v_mov_b32_dpp v173, v63 row_ror:2 row_mask:0xf bank_mask:0xf
	v_mov_b32_e32 v62, v1
	v_mov_b32_e32 v63, v1
	v_mov_b32_dpp v170, v22 row_shr:1 row_mask:0xf bank_mask:0xf
	v_mov_b32_dpp v62, v64 row_ror:1 row_mask:0xf bank_mask:0xf
	v_mov_b32_dpp v63, v65 row_ror:1 row_mask:0xf bank_mask:0xf
	v_mov_b32_dpp v171, v23 row_shr:1 row_mask:0xf bank_mask:0xf
	v_mov_b32_e32 v174, v1
	v_mov_b32_dpp v62, v24 row_shr:1 row_mask:0xf bank_mask:0xf
	v_mov_b32_e32 v175, v1
	v_mov_b32_dpp v63, v25 row_shr:1 row_mask:0xf bank_mask:0xf
	v_mov_b32_dpp v174, v64 row_ror:2 row_mask:0xf bank_mask:0xf
	v_mov_b32_dpp v175, v65 row_ror:2 row_mask:0xf bank_mask:0xf
	v_pk_mul_f32 v[62:63], v[160:161], v[62:63]
	v_pk_mul_f32 v[64:65], v[158:159], v[170:171]
	v_mov_b32_dpp v172, v22 row_shr:2 row_mask:0xf bank_mask:0xf
	v_mov_b32_dpp v173, v23 row_shr:2 row_mask:0xf bank_mask:0xf
	v_mov_b32_dpp v174, v24 row_shr:2 row_mask:0xf bank_mask:0xf
	v_mov_b32_dpp v175, v25 row_shr:2 row_mask:0xf bank_mask:0xf
	v_pk_fma_f32 v[24:25], v[148:149], v[24:25], v[62:63]
	v_pk_fma_f32 v[22:23], v[146:147], v[22:23], v[64:65]
	v_pk_fma_f32 v[24:25], v[144:145], v[174:175], v[24:25]
	v_pk_fma_f32 v[22:23], v[142:143], v[172:173], v[22:23]
	v_pk_add_f32 v[64:65], v[140:141], v[24:25]
	v_pk_add_f32 v[62:63], v[138:139], v[22:23]
	v_mov_b64_e32 v[22:23], v[30:31]
	v_mov_b64_e32 v[24:25], v[32:33]
	s_waitcnt vmcnt(0)
	v_mov_b32_e32 v138, v1
	v_mov_b32_e32 v140, v1
	v_mov_b32_e32 v139, v1
	v_mov_b32_e32 v141, v1
	v_mov_b32_dpp v138, v22 row_ror:1 row_mask:0xf bank_mask:0xf
	v_mov_b32_dpp v140, v22 row_ror:2 row_mask:0xf bank_mask:0xf
	v_mov_b32_dpp v139, v23 row_ror:1 row_mask:0xf bank_mask:0xf
	v_mov_b32_dpp v141, v23 row_ror:2 row_mask:0xf bank_mask:0xf
	v_mov_b32_e32 v22, v1
	v_mov_b32_e32 v23, v1
	v_mov_b32_dpp v138, v26 row_shr:1 row_mask:0xf bank_mask:0xf
	v_mov_b32_dpp v22, v24 row_ror:1 row_mask:0xf bank_mask:0xf
	v_mov_b32_dpp v23, v25 row_ror:1 row_mask:0xf bank_mask:0xf
	v_mov_b32_dpp v139, v27 row_shr:1 row_mask:0xf bank_mask:0xf
	v_mov_b32_e32 v142, v1
	v_mov_b32_dpp v22, v28 row_shr:1 row_mask:0xf bank_mask:0xf
	v_mov_b32_e32 v143, v1
	v_mov_b32_dpp v23, v29 row_shr:1 row_mask:0xf bank_mask:0xf
	v_mov_b32_dpp v142, v24 row_ror:2 row_mask:0xf bank_mask:0xf
	v_mov_b32_dpp v143, v25 row_ror:2 row_mask:0xf bank_mask:0xf
	v_pk_mul_f32 v[22:23], v[168:169], v[22:23]
	v_pk_mul_f32 v[24:25], v[166:167], v[138:139]
	v_mov_b32_dpp v140, v26 row_shr:2 row_mask:0xf bank_mask:0xf
	v_mov_b32_dpp v141, v27 row_shr:2 row_mask:0xf bank_mask:0xf
	v_mov_b32_dpp v142, v28 row_shr:2 row_mask:0xf bank_mask:0xf
	v_mov_b32_dpp v143, v29 row_shr:2 row_mask:0xf bank_mask:0xf
	v_pk_fma_f32 v[22:23], v[164:165], v[28:29], v[22:23]
	v_pk_fma_f32 v[24:25], v[162:163], v[26:27], v[24:25]
	v_pk_fma_f32 v[22:23], v[156:157], v[142:143], v[22:23]
	v_pk_fma_f32 v[26:27], v[154:155], v[140:141], v[24:25]
	v_pk_add_f32 v[24:25], v[152:153], v[22:23]
	v_pk_add_f32 v[22:23], v[150:151], v[26:27]
; __device__ __forceinline__ unsigned cvt_pk_bf16(float lo, float hi) { unsigned r; asm volatile("v_cvt_pk_bf16_f32 %0, %1, %2" : "=v"(r) : "v"(lo), "v"(hi)); return r; }
;     __device__ __forceinline__ void operator()(f32x4 (&acc)[2][2][4][2], const Unit& u, int wr, int wc, int fr, int fq) const {
;     ...
; #pragma unroll
;         for (int blk = 0; blk < 8; ++blk) {
;             const int ai = blk >> 2, bj = (blk >> 1) & 1, n = blk & 1;
;             if (blk < 7) { int chb_ = chb; asm volatile("" : "+v"(chb_));
;                 const int cidx = (((blk + 1) >> 1) & 1) * DFF + chb_ + 4 * ((blk + 1) & 1);
;                 nw0 = *(const f32x4*)(cw + cidx); nw1 = *(const f32x4*)(cw + NUP + cidx); nw2 = *(const f32x4*)(cw + 2 * NUP + cidx); nbb = *(const f32x4*)(cb + cidx); }
;             asm volatile("" : "+v"(w0), "+v"(w1), "+v"(w2), "+v"(bb));
; #pragma unroll
;             for (int m = 3; m >= 0; --m) {
;                 f32x4 v = acc[ai][bj][m][n]; f32x4 pv = (m > 0) ? acc[ai][bj][m > 0 ? m - 1 : 0][n] : (f32x4){0.f, 0.f, 0.f, 0.f};
;                 asm volatile("" : "+v"(v), "+v"(pv));
;                 f32x4 r;
; #pragma unroll
;                 for (int e = 0; e < 4; ++e) {
;                     const float o1 = dppf<0x121>(0.f, pv[e]), o2 = dppf<0x122>(0.f, pv[e]);
;                     const float p1 = dppf<0x111>(o1, v[e]), p2 = dppf<0x112>(o2, v[e]);
;                     r[e] = w2[e] * v[e] + w1[e] * p1 + w0[e] * p2 + bb[e];
;                 }
;                 asm volatile("" : "+v"(r));
;                 acc[ai][bj][m][n] = r;
;             }
;             w0 = nw0; w1 = nw1; w2 = nw2; bb = nbb;
;         }
; #pragma unroll
;         for (int ai = 0; ai < 2; ++ai)
; #pragma unroll
;             for (int m = 0; m < 4; ++m) { int row = u.orow + ai * HALF + wr * 64 + m * 16 + fr; asm volatile("" : "+v"(row)); f32x4 o[2];
; #pragma unroll
;                 for (int n = 0; n < 2; ++n) { const f32x4 g = acc[ai][0][m][n], up = acc[ai][1][m][n];
; #pragma unroll
;                     for (int e = 0; e < 4; ++e) o[n][e] = g[e] * __builtin_amdgcn_rcpf(1.0f + __builtin_amdgcn_exp2f(-1.4426950408889634f * g[e])) * up[e]; }
;                 u32x4 w; w.x = cvt_pk_bf16(o[0][0], o[0][1]); w.y = cvt_pk_bf16(o[0][2], o[0][3]); w.z = cvt_pk_bf16(o[1][0], o[1][1]); w.w = cvt_pk_bf16(o[1][2], o[1][3]);
;                 *(u32x4*)(act + (size_t)row * DFF + chb) = w; }
	v_mov_b64_e32 v[28:29], v[16:17]
	v_mov_b64_e32 v[26:27], v[14:15]
	v_mov_b32_e32 v138, v1
	v_mov_b32_e32 v140, v1
	v_mov_b32_e32 v139, v1
	v_mov_b32_e32 v141, v1
	v_mov_b32_dpp v138, v26 row_ror:1 row_mask:0xf bank_mask:0xf
	v_mov_b32_dpp v140, v26 row_ror:2 row_mask:0xf bank_mask:0xf
	v_mov_b32_dpp v139, v27 row_ror:1 row_mask:0xf bank_mask:0xf
	v_mov_b32_dpp v141, v27 row_ror:2 row_mask:0xf bank_mask:0xf
	v_mov_b32_e32 v26, v1
	v_mov_b32_e32 v27, v1
	v_mov_b32_dpp v138, v30 row_shr:1 row_mask:0xf bank_mask:0xf
	v_mov_b32_dpp v26, v28 row_ror:1 row_mask:0xf bank_mask:0xf
	v_mov_b32_dpp v27, v29 row_ror:1 row_mask:0xf bank_mask:0xf
	v_mov_b32_dpp v139, v31 row_shr:1 row_mask:0xf bank_mask:0xf
	v_mov_b32_e32 v142, v1
	v_mov_b32_dpp v26, v32 row_shr:1 row_mask:0xf bank_mask:0xf
	v_mov_b32_e32 v143, v1
	v_mov_b32_dpp v27, v33 row_shr:1 row_mask:0xf bank_mask:0xf
	v_mov_b32_dpp v142, v28 row_ror:2 row_mask:0xf bank_mask:0xf
	v_mov_b32_dpp v143, v29 row_ror:2 row_mask:0xf bank_mask:0xf
	v_pk_mul_f32 v[28:29], v[166:167], v[138:139]
	v_pk_mul_f32 v[26:27], v[168:169], v[26:27]
	v_mov_b32_dpp v140, v30 row_shr:2 row_mask:0xf bank_mask:0xf
	v_mov_b32_dpp v141, v31 row_shr:2 row_mask:0xf bank_mask:0xf
	v_mov_b32_dpp v142, v32 row_shr:2 row_mask:0xf bank_mask:0xf
	v_mov_b32_dpp v143, v33 row_shr:2 row_mask:0xf bank_mask:0xf
	v_pk_fma_f32 v[26:27], v[164:165], v[32:33], v[26:27]
	v_pk_fma_f32 v[28:29], v[162:163], v[30:31], v[28:29]
	v_pk_fma_f32 v[26:27], v[156:157], v[142:143], v[26:27]
	v_pk_fma_f32 v[30:31], v[154:155], v[140:141], v[28:29]
	v_pk_add_f32 v[28:29], v[152:153], v[26:27]
	v_pk_add_f32 v[26:27], v[150:151], v[30:31]
	v_mov_b64_e32 v[32:33], v[8:9]
	v_mov_b64_e32 v[30:31], v[6:7]
	v_mov_b32_e32 v138, v1
	v_mov_b32_e32 v140, v1
	v_mov_b32_e32 v139, v1
	v_mov_b32_e32 v141, v1
	v_mov_b32_dpp v138, v30 row_ror:1 row_mask:0xf bank_mask:0xf
	v_mov_b32_dpp v140, v30 row_ror:2 row_mask:0xf bank_mask:0xf
	v_mov_b32_dpp v139, v31 row_ror:1 row_mask:0xf bank_mask:0xf
	v_mov_b32_dpp v141, v31 row_ror:2 row_mask:0xf bank_mask:0xf
	v_mov_b32_e32 v30, v1
	v_mov_b32_e32 v31, v1
	v_mov_b32_dpp v138, v14 row_shr:1 row_mask:0xf bank_mask:0xf
	v_mov_b32_dpp v30, v32 row_ror:1 row_mask:0xf bank_mask:0xf
	v_mov_b32_dpp v31, v33 row_ror:1 row_mask:0xf bank_mask:0xf
	v_mov_b32_dpp v139, v15 row_shr:1 row_mask:0xf bank_mask:0xf
	v_mov_b32_e32 v142, v1
	v_mov_b32_dpp v30, v16 row_shr:1 row_mask:0xf bank_mask:0xf
	v_mov_b32_e32 v143, v1
	v_mov_b32_dpp v31, v17 row_shr:1 row_mask:0xf bank_mask:0xf
	v_mov_b32_dpp v142, v32 row_ror:2 row_mask:0xf bank_mask:0xf
	v_mov_b32_dpp v143, v33 row_ror:2 row_mask:0xf bank_mask:0xf
	v_pk_mul_f32 v[30:31], v[168:169], v[30:31]
	v_pk_mul_f32 v[32:33], v[166:167], v[138:139]
	v_mov_b32_dpp v140, v14 row_shr:2 row_mask:0xf bank_mask:0xf
	v_mov_b32_dpp v141, v15 row_shr:2 row_mask:0xf bank_mask:0xf
	v_mov_b32_dpp v142, v16 row_shr:2 row_mask:0xf bank_mask:0xf
	v_mov_b32_dpp v143, v17 row_shr:2 row_mask:0xf bank_mask:0xf
	v_pk_fma_f32 v[16:17], v[164:165], v[16:17], v[30:31]
	v_pk_fma_f32 v[14:15], v[162:163], v[14:15], v[32:33]
	v_mov_b64_e32 v[108:109], s[2:3]
	v_pk_fma_f32 v[14:15], v[154:155], v[140:141], v[14:15]
	v_pk_fma_f32 v[16:17], v[156:157], v[142:143], v[16:17]
	v_mov_b64_e32 v[106:107], s[0:1]
	v_pk_add_f32 v[16:17], v[152:153], v[16:17]
	v_pk_add_f32 v[14:15], v[150:151], v[14:15]
	v_mov_b32_e32 v30, v1
	v_mov_b32_e32 v31, v1
	v_mov_b32_e32 v32, v1
	v_mov_b32_e32 v33, v1
	v_mov_b32_dpp v30, v106 row_ror:1 row_mask:0xf bank_mask:0xf
	v_mov_b32_dpp v31, v107 row_ror:1 row_mask:0xf bank_mask:0xf
	v_mov_b32_dpp v32, v106 row_ror:2 row_mask:0xf bank_mask:0xf
	v_mov_b32_dpp v30, v6 row_shr:1 row_mask:0xf bank_mask:0xf
	v_mov_b32_dpp v31, v7 row_shr:1 row_mask:0xf bank_mask:0xf
	v_mov_b32_dpp v33, v107 row_ror:2 row_mask:0xf bank_mask:0xf
	v_pk_mul_f32 v[30:31], v[166:167], v[30:31]
	v_mov_b32_dpp v32, v6 row_shr:2 row_mask:0xf bank_mask:0xf
	v_mov_b32_dpp v33, v7 row_shr:2 row_mask:0xf bank_mask:0xf
	v_pk_fma_f32 v[6:7], v[162:163], v[6:7], v[30:31]
	v_mul_f32_e32 v30, 0xbfb8aa3b, v102
	v_exp_f32_e32 v30, v30
	v_pk_fma_f32 v[6:7], v[154:155], v[32:33], v[6:7]
	v_mul_f32_e32 v32, 0xbfb8aa3b, v104
	v_exp_f32_e32 v32, v32
	v_add_f32_e32 v30, 1.0, v30
	v_rcp_f32_e32 v30, v30
	v_mul_f32_e32 v33, 0xbfb8aa3b, v105
	v_add_f32_e32 v32, 1.0, v32
	v_rcp_f32_e32 v32, v32
	v_mul_f32_e32 v30, v102, v30
	v_mul_f32_e32 v102, 0xbfb8aa3b, v118
	v_exp_f32_e32 v102, v102
	v_mul_f32_e32 v32, v104, v32
	v_exp_f32_e32 v33, v33
	v_mov_b32_e32 v106, v1
	v_add_f32_e32 v102, 1.0, v102
	v_rcp_f32_e32 v102, v102
	v_add_f32_e32 v33, 1.0, v33
	v_rcp_f32_e32 v33, v33
	v_mov_b32_e32 v107, v1
	v_mul_f32_e32 v102, v118, v102
	v_mul_f32_e32 v104, v102, v130
	v_mul_f32_e32 v102, 0xbfb8aa3b, v119
	v_exp_f32_e32 v102, v102
	v_mul_f32_e32 v33, v105, v33
	v_mov_b32_dpp v106, v108 row_ror:1 row_mask:0xf bank_mask:0xf
	v_mov_b32_dpp v107, v109 row_ror:1 row_mask:0xf bank_mask:0xf
	v_add_f32_e32 v102, 1.0, v102
	v_rcp_f32_e32 v102, v102
	v_mov_b32_e32 v138, v1
	v_mov_b32_dpp v106, v8 row_shr:1 row_mask:0xf bank_mask:0xf
	v_mov_b32_e32 v139, v1
	v_mul_f32_e32 v102, v119, v102
	v_mul_f32_e32 v105, v102, v131
	v_mul_f32_e32 v102, 0xbfb8aa3b, v120
	v_exp_f32_e32 v102, v102
	v_mov_b32_dpp v107, v9 row_shr:1 row_mask:0xf bank_mask:0xf
	v_mov_b32_dpp v138, v108 row_ror:2 row_mask:0xf bank_mask:0xf
	v_mov_b32_dpp v139, v109 row_ror:2 row_mask:0xf bank_mask:0xf
	v_add_f32_e32 v102, 1.0, v102
	v_rcp_f32_e32 v102, v102
	v_pk_mul_f32 v[106:107], v[168:169], v[106:107]
	v_mul_f32_e32 v31, 0xbfb8aa3b, v103
	v_mov_b32_dpp v138, v8 row_shr:2 row_mask:0xf bank_mask:0xf
; __device__ __forceinline__ unsigned cvt_pk_bf16(float lo, float hi) { unsigned r; asm volatile("v_cvt_pk_bf16_f32 %0, %1, %2" : "=v"(r) : "v"(lo), "v"(hi)); return r; }
;     __device__ __forceinline__ void operator()(f32x4 (&acc)[2][2][4][2], const Unit& u, int wr, int wc, int fr, int fq) const {
;     ...
; #pragma unroll
;         for (int ai = 0; ai < 2; ++ai)
; #pragma unroll
;             for (int m = 0; m < 4; ++m) { int row = u.orow + ai * HALF + wr * 64 + m * 16 + fr; asm volatile("" : "+v"(row)); f32x4 o[2];
; #pragma unroll
;                 for (int n = 0; n < 2; ++n) { const f32x4 g = acc[ai][0][m][n], up = acc[ai][1][m][n];
; #pragma unroll
;                     for (int e = 0; e < 4; ++e) o[n][e] = g[e] * __builtin_amdgcn_rcpf(1.0f + __builtin_amdgcn_exp2f(-1.4426950408889634f * g[e])) * up[e]; }
;                 u32x4 w; w.x = cvt_pk_bf16(o[0][0], o[0][1]); w.y = cvt_pk_bf16(o[0][2], o[0][3]); w.z = cvt_pk_bf16(o[1][0], o[1][1]); w.w = cvt_pk_bf16(o[1][2], o[1][3]);
;                 *(u32x4*)(act + (size_t)row * DFF + chb) = w; }
	v_mul_f32_e32 v102, v120, v102
	v_mov_b32_dpp v139, v9 row_shr:2 row_mask:0xf bank_mask:0xf
	v_pk_fma_f32 v[8:9], v[164:165], v[8:9], v[106:107]
	v_exp_f32_e32 v31, v31
	v_mul_f32_e32 v106, v102, v132
	v_mul_f32_e32 v102, 0xbfb8aa3b, v121
	v_exp_f32_e32 v102, v102
	v_add_f32_e32 v31, 1.0, v31
	v_rcp_f32_e32 v31, v31
	v_pk_fma_f32 v[8:9], v[156:157], v[138:139], v[8:9]
	v_add_f32_e32 v102, 1.0, v102
	v_rcp_f32_e32 v102, v102
	v_mul_f32_e32 v31, v103, v31
	v_readlane_b32 s0, v254, 28
	v_pk_add_f32 v[8:9], v[152:153], v[8:9]
	v_pk_add_f32 v[6:7], v[150:151], v[6:7]
	v_mul_f32_e32 v30, v30, v134
	v_mul_f32_e32 v31, v31, v135
	v_mul_f32_e32 v102, v121, v102
	v_readlane_b32 s1, v254, 29
	v_mul_f32_e32 v32, v32, v136
	v_mul_f32_e32 v33, v33, v137
	v_mul_f32_e32 v107, v102, v133
	v_cvt_pk_bf16_f32 v102, v30, v31
	v_mov_b64_e32 v[30:31], s[0:1]
	s_movk_i32 s2, 0x2c00
	v_cvt_pk_bf16_f32 v103, v32, v33
	v_cvt_pk_bf16_f32 v104, v104, v105
	v_cvt_pk_bf16_f32 v105, v106, v107
	v_mad_i64_i32 v[106:107], s[0:1], v212, s2, v[30:31]
	v_lshlrev_b64 v[32:33], 1, v[214:215]
	v_lshl_add_u64 v[106:107], v[106:107], 0, v[32:33]
	global_store_dwordx4 v[106:107], v[102:105], off nt
	s_andn2_b64 vcc, exec, s[46:47]
	s_nop 0
	v_mul_f32_e32 v102, 0xbfb8aa3b, v70
	v_exp_f32_e32 v102, v102
	s_nop 0
	v_add_f32_e32 v102, 1.0, v102
	v_rcp_f32_e32 v102, v102
	s_nop 0
	v_mul_f32_e32 v70, v70, v102
	v_mul_f32_e32 v102, 0xbfb8aa3b, v71
	v_exp_f32_e32 v102, v102
	v_mul_f32_e32 v70, v70, v122
	v_add_f32_e32 v102, 1.0, v102
	v_rcp_f32_e32 v102, v102
	s_nop 0
	v_mul_f32_e32 v71, v71, v102
	v_mul_f32_e32 v102, 0xbfb8aa3b, v72
	v_exp_f32_e32 v102, v102
	v_mul_f32_e32 v71, v71, v123
	v_cvt_pk_bf16_f32 v70, v70, v71
	v_add_f32_e32 v102, 1.0, v102
	v_rcp_f32_e32 v102, v102
	s_nop 0
	v_mul_f32_e32 v72, v72, v102
	v_mul_f32_e32 v102, 0xbfb8aa3b, v73
	v_exp_f32_e32 v102, v102
	v_mul_f32_e32 v72, v72, v124
	v_add_f32_e32 v102, 1.0, v102
	v_rcp_f32_e32 v102, v102
	s_nop 0
	v_mul_f32_e32 v73, v73, v102
	v_mul_f32_e32 v102, 0xbfb8aa3b, v86
	v_exp_f32_e32 v102, v102
	v_mul_f32_e32 v73, v73, v125
	v_cvt_pk_bf16_f32 v71, v72, v73
	v_add_f32_e32 v102, 1.0, v102
	v_rcp_f32_e32 v102, v102
	s_nop 0
	v_mul_f32_e32 v86, v86, v102
	v_mul_f32_e32 v102, 0xbfb8aa3b, v87
	v_exp_f32_e32 v102, v102
	v_mul_f32_e32 v86, v86, v126
	v_add_f32_e32 v102, 1.0, v102
	v_rcp_f32_e32 v102, v102
	s_nop 0
	v_mul_f32_e32 v87, v87, v102
	v_mul_f32_e32 v102, 0xbfb8aa3b, v88
	v_exp_f32_e32 v102, v102
	v_mul_f32_e32 v87, v87, v127
	v_cvt_pk_bf16_f32 v72, v86, v87
	v_mad_i64_i32 v[86:87], s[0:1], v210, s2, v[30:31]
	v_add_f32_e32 v102, 1.0, v102
	v_rcp_f32_e32 v102, v102
	v_lshl_add_u64 v[86:87], v[86:87], 0, v[32:33]
	v_mul_f32_e32 v88, v88, v102
	v_mul_f32_e32 v102, 0xbfb8aa3b, v89
	v_exp_f32_e32 v102, v102
	v_mul_f32_e32 v88, v88, v128
	v_add_f32_e32 v102, 1.0, v102
	v_rcp_f32_e32 v102, v102
	s_nop 0
	v_mul_f32_e32 v89, v89, v102
	v_mul_f32_e32 v89, v89, v129
	v_cvt_pk_bf16_f32 v73, v88, v89
	global_store_dwordx4 v[86:87], v[70:73], off nt
	s_nop 1
	v_mul_f32_e32 v70, 0xbfb8aa3b, v34
	v_exp_f32_e32 v70, v70
	s_nop 0
	v_add_f32_e32 v70, 1.0, v70
	v_rcp_f32_e32 v70, v70
	s_nop 0
	v_mul_f32_e32 v34, v34, v70
	v_mul_f32_e32 v70, 0xbfb8aa3b, v35
	v_exp_f32_e32 v70, v70
	v_mul_f32_e32 v34, v34, v98
	v_add_f32_e32 v70, 1.0, v70
	v_rcp_f32_e32 v70, v70
	s_nop 0
	v_mul_f32_e32 v35, v35, v70
	v_mul_f32_e32 v70, 0xbfb8aa3b, v36
	v_exp_f32_e32 v70, v70
	v_mul_f32_e32 v35, v35, v99
	v_cvt_pk_bf16_f32 v34, v34, v35
	v_add_f32_e32 v70, 1.0, v70
	v_rcp_f32_e32 v70, v70
	s_nop 0
	v_mul_f32_e32 v36, v36, v70
	v_mul_f32_e32 v70, 0xbfb8aa3b, v37
	v_exp_f32_e32 v70, v70
	v_mul_f32_e32 v36, v36, v100
	v_add_f32_e32 v70, 1.0, v70
	v_rcp_f32_e32 v70, v70
	s_nop 0
	v_mul_f32_e32 v37, v37, v70
	v_mul_f32_e32 v70, 0xbfb8aa3b, v54
	v_exp_f32_e32 v70, v70
	v_mul_f32_e32 v37, v37, v101
	v_cvt_pk_bf16_f32 v35, v36, v37
	v_add_f32_e32 v70, 1.0, v70
	v_rcp_f32_e32 v70, v70
	s_nop 0
	v_mul_f32_e32 v54, v54, v70
	v_mul_f32_e32 v70, 0xbfb8aa3b, v55
	v_exp_f32_e32 v70, v70
	v_mul_f32_e32 v54, v54, v110
	v_add_f32_e32 v70, 1.0, v70
	v_rcp_f32_e32 v70, v70
	s_nop 0
	v_mul_f32_e32 v55, v55, v70
	v_mul_f32_e32 v70, 0xbfb8aa3b, v56
	v_exp_f32_e32 v70, v70
	v_mul_f32_e32 v55, v55, v111
	v_cvt_pk_bf16_f32 v36, v54, v55
	v_mad_i64_i32 v[54:55], s[0:1], v208, s2, v[30:31]
	v_add_f32_e32 v70, 1.0, v70
	v_rcp_f32_e32 v70, v70
	v_lshl_add_u64 v[54:55], v[54:55], 0, v[32:33]
	v_mul_f32_e32 v56, v56, v70
	v_mul_f32_e32 v70, 0xbfb8aa3b, v57
	v_exp_f32_e32 v70, v70
	v_mul_f32_e32 v56, v56, v112
	v_add_f32_e32 v70, 1.0, v70
	v_rcp_f32_e32 v70, v70
	s_nop 0
	v_mul_f32_e32 v57, v57, v70
	v_mul_f32_e32 v57, v57, v113
	v_cvt_pk_bf16_f32 v37, v56, v57
	global_store_dwordx4 v[54:55], v[34:37], off nt
	s_nop 1
	v_mul_f32_e32 v34, 0xbfb8aa3b, v2
	v_exp_f32_e32 v34, v34
	s_nop 0
	v_add_f32_e32 v34, 1.0, v34
	v_rcp_f32_e32 v34, v34
	s_nop 0
	v_mul_f32_e32 v2, v2, v34
	v_mul_f32_e32 v34, 0xbfb8aa3b, v3
	v_exp_f32_e32 v34, v34
	v_mul_f32_e32 v2, v2, v66
	v_add_f32_e32 v34, 1.0, v34
	v_rcp_f32_e32 v34, v34
	s_nop 0
	v_mul_f32_e32 v3, v3, v34
	v_mul_f32_e32 v34, 0xbfb8aa3b, v4
	v_exp_f32_e32 v34, v34
	v_mul_f32_e32 v3, v3, v67
	v_cvt_pk_bf16_f32 v2, v2, v3
	v_add_f32_e32 v34, 1.0, v34
	v_rcp_f32_e32 v34, v34
	s_nop 0
	v_mul_f32_e32 v4, v4, v34
	v_mul_f32_e32 v34, 0xbfb8aa3b, v5
	v_exp_f32_e32 v34, v34
	v_mul_f32_e32 v4, v4, v68
	v_add_f32_e32 v34, 1.0, v34
	v_rcp_f32_e32 v34, v34
	s_nop 0
	v_mul_f32_e32 v5, v5, v34
	v_mul_f32_e32 v34, 0xbfb8aa3b, v10
	v_exp_f32_e32 v34, v34
	v_mul_f32_e32 v5, v5, v69
	v_cvt_pk_bf16_f32 v3, v4, v5
	v_add_f32_e32 v34, 1.0, v34
	v_rcp_f32_e32 v34, v34
; __device__ __forceinline__ unsigned cvt_pk_bf16(float lo, float hi) { unsigned r; asm volatile("v_cvt_pk_bf16_f32 %0, %1, %2" : "=v"(r) : "v"(lo), "v"(hi)); return r; }
;     __device__ __forceinline__ void operator()(f32x4 (&acc)[2][2][4][2], const Unit& u, int wr, int wc, int fr, int fq) const {
;     ...
; #pragma unroll
;         for (int ai = 0; ai < 2; ++ai)
; #pragma unroll
;             for (int m = 0; m < 4; ++m) { int row = u.orow + ai * HALF + wr * 64 + m * 16 + fr; asm volatile("" : "+v"(row)); f32x4 o[2];
; #pragma unroll
;                 for (int n = 0; n < 2; ++n) { const f32x4 g = acc[ai][0][m][n], up = acc[ai][1][m][n];
; #pragma unroll
;                     for (int e = 0; e < 4; ++e) o[n][e] = g[e] * __builtin_amdgcn_rcpf(1.0f + __builtin_amdgcn_exp2f(-1.4426950408889634f * g[e])) * up[e]; }
;                 u32x4 w; w.x = cvt_pk_bf16(o[0][0], o[0][1]); w.y = cvt_pk_bf16(o[0][2], o[0][3]); w.z = cvt_pk_bf16(o[1][0], o[1][1]); w.w = cvt_pk_bf16(o[1][2], o[1][3]);
;                 *(u32x4*)(act + (size_t)row * DFF + chb) = w; }
	s_nop 0
	v_mul_f32_e32 v10, v10, v34
	v_mul_f32_e32 v34, 0xbfb8aa3b, v11
	v_exp_f32_e32 v34, v34
	v_mul_f32_e32 v10, v10, v82
	v_add_f32_e32 v34, 1.0, v34
	v_rcp_f32_e32 v34, v34
	s_nop 0
	v_mul_f32_e32 v11, v11, v34
	v_mul_f32_e32 v34, 0xbfb8aa3b, v12
	v_exp_f32_e32 v34, v34
	v_mul_f32_e32 v11, v11, v83
	v_cvt_pk_bf16_f32 v4, v10, v11
	v_mad_i64_i32 v[10:11], s[0:1], v206, s2, v[30:31]
	v_add_f32_e32 v34, 1.0, v34
	v_rcp_f32_e32 v34, v34
	v_lshl_add_u64 v[10:11], v[10:11], 0, v[32:33]
	v_mul_f32_e32 v12, v12, v34
	v_mul_f32_e32 v34, 0xbfb8aa3b, v13
	v_exp_f32_e32 v34, v34
	v_mul_f32_e32 v12, v12, v84
	v_add_f32_e32 v34, 1.0, v34
	v_rcp_f32_e32 v34, v34
	s_nop 0
	v_mul_f32_e32 v13, v13, v34
	v_mul_f32_e32 v13, v13, v85
	v_cvt_pk_bf16_f32 v5, v12, v13
	global_store_dwordx4 v[10:11], v[2:5], off nt
	v_mul_f32_e32 v10, 0xbfb8aa3b, v90
	v_exp_f32_e32 v10, v10
	v_mul_f32_e32 v2, 0xbfb8aa3b, v114
	v_mul_f32_e32 v3, 0xbfb8aa3b, v115
	v_mul_f32_e32 v4, 0xbfb8aa3b, v116
	v_add_f32_e32 v10, 1.0, v10
	v_rcp_f32_e32 v10, v10
	v_exp_f32_e32 v2, v2
	v_exp_f32_e32 v3, v3
	v_exp_f32_e32 v4, v4
	v_mul_f32_e32 v10, v90, v10
	v_mul_f32_e32 v6, v10, v6
	v_mul_f32_e32 v10, 0xbfb8aa3b, v91
	v_exp_f32_e32 v10, v10
	v_mul_f32_e32 v5, 0xbfb8aa3b, v117
	v_exp_f32_e32 v5, v5
	v_add_f32_e32 v2, 1.0, v2
	v_add_f32_e32 v10, 1.0, v10
	v_rcp_f32_e32 v10, v10
	v_add_f32_e32 v3, 1.0, v3
	v_add_f32_e32 v4, 1.0, v4
	v_rcp_f32_e32 v2, v2
	v_mul_f32_e32 v10, v91, v10
	v_mul_f32_e32 v7, v10, v7
	v_mul_f32_e32 v10, 0xbfb8aa3b, v92
	v_exp_f32_e32 v10, v10
	v_rcp_f32_e32 v3, v3
	v_rcp_f32_e32 v4, v4
	v_add_f32_e32 v5, 1.0, v5
	v_add_f32_e32 v10, 1.0, v10
	v_rcp_f32_e32 v10, v10
	v_rcp_f32_e32 v5, v5
	v_mul_f32_e32 v2, v114, v2
	v_mul_f32_e32 v3, v115, v3
	v_mul_f32_e32 v10, v92, v10
	v_mul_f32_e32 v8, v10, v8
	v_mul_f32_e32 v10, 0xbfb8aa3b, v93
	v_exp_f32_e32 v10, v10
	v_mul_f32_e32 v4, v116, v4
	v_mul_f32_e32 v2, v2, v62
	v_mul_f32_e32 v3, v3, v63
	v_add_f32_e32 v10, 1.0, v10
	v_rcp_f32_e32 v10, v10
	v_mul_f32_e32 v4, v4, v64
	v_mul_f32_e32 v5, v117, v5
	v_mul_f32_e32 v5, v5, v65
	v_cvt_pk_bf16_f32 v2, v2, v3
	v_cvt_pk_bf16_f32 v3, v4, v5
	v_cvt_pk_bf16_f32 v4, v6, v7
	v_mad_i64_i32 v[6:7], s[0:1], v204, s2, v[30:31]
	v_mul_f32_e32 v10, v93, v10
	v_lshl_add_u64 v[6:7], v[6:7], 0, v[32:33]
	v_mul_f32_e32 v9, v10, v9
	v_cvt_pk_bf16_f32 v5, v8, v9
	global_store_dwordx4 v[6:7], v[2:5], off nt
	v_mul_f32_e32 v6, 0xbfb8aa3b, v78
	v_mul_f32_e32 v7, 0xbfb8aa3b, v79
	v_mul_f32_e32 v2, 0xbfb8aa3b, v94
	v_mul_f32_e32 v3, 0xbfb8aa3b, v95
	v_mul_f32_e32 v4, 0xbfb8aa3b, v96
	v_exp_f32_e32 v2, v2
	v_exp_f32_e32 v3, v3
	v_exp_f32_e32 v4, v4
	v_mul_f32_e32 v5, 0xbfb8aa3b, v97
	v_exp_f32_e32 v6, v6
	v_exp_f32_e32 v7, v7
	v_exp_f32_e32 v5, v5
	v_mul_f32_e32 v8, 0xbfb8aa3b, v80
	v_mul_f32_e32 v9, 0xbfb8aa3b, v81
	v_exp_f32_e32 v8, v8
	v_exp_f32_e32 v9, v9
	v_add_f32_e32 v2, 1.0, v2
	v_add_f32_e32 v3, 1.0, v3
	v_add_f32_e32 v4, 1.0, v4
	v_add_f32_e32 v6, 1.0, v6
	v_add_f32_e32 v7, 1.0, v7
	v_rcp_f32_e32 v2, v2
	v_rcp_f32_e32 v3, v3
	v_rcp_f32_e32 v4, v4
	v_add_f32_e32 v5, 1.0, v5
	v_rcp_f32_e32 v6, v6
	v_rcp_f32_e32 v7, v7
	v_rcp_f32_e32 v5, v5
	v_add_f32_e32 v8, 1.0, v8
	v_add_f32_e32 v9, 1.0, v9
	v_rcp_f32_e32 v8, v8
	v_rcp_f32_e32 v9, v9
	v_mul_f32_e32 v2, v94, v2
	v_mul_f32_e32 v3, v95, v3
	v_mul_f32_e32 v4, v96, v4
	v_mul_f32_e32 v6, v78, v6
	v_mul_f32_e32 v7, v79, v7
	v_mul_f32_e32 v2, v2, v42
	v_mul_f32_e32 v3, v3, v43
	v_mul_f32_e32 v4, v4, v44
	v_mul_f32_e32 v5, v97, v5
	v_mul_f32_e32 v6, v6, v14
	v_mul_f32_e32 v7, v7, v15
	v_mul_f32_e32 v5, v5, v45
; __device__ __forceinline__ unsigned cvt_pk_bf16(float lo, float hi) { unsigned r; asm volatile("v_cvt_pk_bf16_f32 %0, %1, %2" : "=v"(r) : "v"(lo), "v"(hi)); return r; }
; #define PG8_BAR __builtin_amdgcn_s_barrier()
;     __device__ __forceinline__ void operator()(f32x4 (&acc)[2][2][4][2], const Unit& u, int wr, int wc, int fr, int fq) const {
;     ...
; #pragma unroll
;         for (int ai = 0; ai < 2; ++ai)
; #pragma unroll
;             for (int m = 0; m < 4; ++m) { int row = u.orow + ai * HALF + wr * 64 + m * 16 + fr; asm volatile("" : "+v"(row)); f32x4 o[2];
; #pragma unroll
;                 for (int n = 0; n < 2; ++n) { const f32x4 g = acc[ai][0][m][n], up = acc[ai][1][m][n];
; #pragma unroll
;                     for (int e = 0; e < 4; ++e) o[n][e] = g[e] * __builtin_amdgcn_rcpf(1.0f + __builtin_amdgcn_exp2f(-1.4426950408889634f * g[e])) * up[e]; }
;                 u32x4 w; w.x = cvt_pk_bf16(o[0][0], o[0][1]); w.y = cvt_pk_bf16(o[0][2], o[0][3]); w.z = cvt_pk_bf16(o[1][0], o[1][1]); w.w = cvt_pk_bf16(o[1][2], o[1][3]);
;                 *(u32x4*)(act + (size_t)row * DFF + chb) = w; }
; template <class Epi, class Sched>
; __device__ __forceinline__ void gemm_phase(LAS unsigned char* lds, const Gemm g, const Sched& S, const Epi& E, int wave_id) {
;     ...
;         if (wr == 0) PG8_BAR;
;         E(acc, cur, wr, wc, fr, fq);
;         if (!has_next) break;
; #pragma unroll
;         for (int a = 0; a < 2; ++a)
; #pragma unroll
;             for (int b = 0; b < 2; ++b)
; #pragma unroll
;                 for (int m = 0; m < 4; ++m)
; #pragma unroll
;                     for (int n = 0; n < 2; ++n) acc[a][b][m][n] = (f32x4){0.f, 0.f, 0.f, 0.f};
;         cur = nxt; cA = nA; cB = nB; ++ui;
;         if (wr == 1) PG8_BAR;
	v_cvt_pk_bf16_f32 v2, v2, v3
	v_cvt_pk_bf16_f32 v3, v4, v5
	v_cvt_pk_bf16_f32 v4, v6, v7
	v_mad_i64_i32 v[6:7], s[0:1], v202, s2, v[30:31]
	v_mul_f32_e32 v8, v80, v8
	v_mul_f32_e32 v9, v81, v9
	v_lshl_add_u64 v[6:7], v[6:7], 0, v[32:33]
	v_mul_f32_e32 v8, v8, v16
	v_mul_f32_e32 v9, v9, v17
	v_cvt_pk_bf16_f32 v5, v8, v9
	global_store_dwordx4 v[6:7], v[2:5], off nt
	v_mul_f32_e32 v6, 0xbfb8aa3b, v74
	v_mul_f32_e32 v7, 0xbfb8aa3b, v75
	v_mul_f32_e32 v2, 0xbfb8aa3b, v58
	v_mul_f32_e32 v3, 0xbfb8aa3b, v59
	v_mul_f32_e32 v4, 0xbfb8aa3b, v60
	v_exp_f32_e32 v2, v2
	v_exp_f32_e32 v3, v3
	v_exp_f32_e32 v4, v4
	v_mul_f32_e32 v5, 0xbfb8aa3b, v61
	v_exp_f32_e32 v6, v6
	v_exp_f32_e32 v7, v7
	v_exp_f32_e32 v5, v5
	v_mul_f32_e32 v8, 0xbfb8aa3b, v76
	v_mul_f32_e32 v9, 0xbfb8aa3b, v77
	v_exp_f32_e32 v8, v8
	v_exp_f32_e32 v9, v9
	v_add_f32_e32 v2, 1.0, v2
	v_add_f32_e32 v3, 1.0, v3
	v_add_f32_e32 v4, 1.0, v4
	v_add_f32_e32 v6, 1.0, v6
	v_add_f32_e32 v7, 1.0, v7
	v_rcp_f32_e32 v2, v2
	v_rcp_f32_e32 v3, v3
	v_rcp_f32_e32 v4, v4
	v_add_f32_e32 v5, 1.0, v5
	v_rcp_f32_e32 v6, v6
	v_rcp_f32_e32 v7, v7
	v_rcp_f32_e32 v5, v5
	v_add_f32_e32 v8, 1.0, v8
	v_add_f32_e32 v9, 1.0, v9
	v_rcp_f32_e32 v8, v8
	v_rcp_f32_e32 v9, v9
	v_mul_f32_e32 v2, v58, v2
	v_mul_f32_e32 v3, v59, v3
	v_mul_f32_e32 v4, v60, v4
	v_mul_f32_e32 v6, v74, v6
	v_mul_f32_e32 v7, v75, v7
	v_mul_f32_e32 v2, v2, v50
	v_mul_f32_e32 v3, v3, v51
	v_mul_f32_e32 v4, v4, v52
	v_mul_f32_e32 v5, v61, v5
	v_mul_f32_e32 v6, v6, v26
	v_mul_f32_e32 v7, v7, v27
	v_mul_f32_e32 v5, v5, v53
	v_cvt_pk_bf16_f32 v2, v2, v3
	v_cvt_pk_bf16_f32 v3, v4, v5
	v_cvt_pk_bf16_f32 v4, v6, v7
	v_mad_i64_i32 v[6:7], s[0:1], v200, s2, v[30:31]
	v_mul_f32_e32 v8, v76, v8
	v_mul_f32_e32 v9, v77, v9
	v_lshl_add_u64 v[6:7], v[6:7], 0, v[32:33]
	v_mul_f32_e32 v8, v8, v28
	v_mul_f32_e32 v9, v9, v29
	v_cvt_pk_bf16_f32 v5, v8, v9
	global_store_dwordx4 v[6:7], v[2:5], off nt
	v_mul_f32_e32 v6, 0xbfb8aa3b, v38
	v_mul_f32_e32 v7, 0xbfb8aa3b, v39
	v_mul_f32_e32 v2, 0xbfb8aa3b, v18
	v_mul_f32_e32 v3, 0xbfb8aa3b, v19
	v_mul_f32_e32 v4, 0xbfb8aa3b, v20
	v_exp_f32_e32 v2, v2
	v_exp_f32_e32 v3, v3
	v_exp_f32_e32 v4, v4
	v_mul_f32_e32 v5, 0xbfb8aa3b, v21
	v_exp_f32_e32 v6, v6
	v_exp_f32_e32 v7, v7
	v_exp_f32_e32 v5, v5
	v_mul_f32_e32 v8, 0xbfb8aa3b, v40
	v_mul_f32_e32 v9, 0xbfb8aa3b, v41
	v_exp_f32_e32 v8, v8
	v_exp_f32_e32 v9, v9
	v_add_f32_e32 v2, 1.0, v2
	v_add_f32_e32 v3, 1.0, v3
	v_add_f32_e32 v4, 1.0, v4
	v_add_f32_e32 v6, 1.0, v6
	v_add_f32_e32 v7, 1.0, v7
	v_rcp_f32_e32 v2, v2
	v_rcp_f32_e32 v3, v3
	v_rcp_f32_e32 v4, v4
	v_add_f32_e32 v5, 1.0, v5
	v_rcp_f32_e32 v6, v6
	v_rcp_f32_e32 v7, v7
	v_rcp_f32_e32 v5, v5
	v_add_f32_e32 v8, 1.0, v8
	v_add_f32_e32 v9, 1.0, v9
	v_rcp_f32_e32 v8, v8
	v_rcp_f32_e32 v9, v9
	v_mul_f32_e32 v2, v18, v2
	v_mul_f32_e32 v3, v19, v3
	v_mul_f32_e32 v4, v20, v4
	v_mul_f32_e32 v6, v38, v6
	v_mul_f32_e32 v7, v39, v7
	v_mul_f32_e32 v2, v2, v46
	v_mul_f32_e32 v3, v3, v47
	v_mul_f32_e32 v4, v4, v48
	v_mul_f32_e32 v5, v21, v5
	v_mul_f32_e32 v6, v6, v22
	v_mul_f32_e32 v7, v7, v23
	v_mul_f32_e32 v5, v5, v49
	v_cvt_pk_bf16_f32 v2, v2, v3
	v_cvt_pk_bf16_f32 v3, v4, v5
	v_cvt_pk_bf16_f32 v4, v6, v7
	v_mad_i64_i32 v[6:7], s[0:1], v198, s2, v[30:31]
	v_mul_f32_e32 v8, v40, v8
	v_mul_f32_e32 v9, v41, v9
	v_lshl_add_u64 v[6:7], v[6:7], 0, v[32:33]
	s_mov_b64 s[2:3], -1
	v_mul_f32_e32 v8, v8, v24
	v_mul_f32_e32 v9, v9, v25
	v_cvt_pk_bf16_f32 v5, v8, v9
	global_store_dwordx4 v[6:7], v[2:5], off nt
	s_cbranch_vccnz .LBB0_973
	s_andn2_b64 vcc, exec, s[4:5]
	s_cbranch_vccnz .LBB0_972
	s_barrier
	s_branch .LBB0_972
